# branch-merge seam hook and final epilogue: 191 redundant canonicalising v_max x,x,x before fmaxf(x,1e-20) removed (hazard distances kept)
# baseline (speedup 1.0000x reference)
;     static __device__ __forceinline__ void unpack(const u32x4 g4, f32x4& g0, f32x4& g1) { g0 = (f32x4){bflo(g4.x), bfhi(g4.x), bflo(g4.y), bfhi(g4.y)}; g1 = (f32x4){bflo(g4.z), bfhi(g4.z), bflo(g4.w), bfhi(g4.w)}; }
;     __device__ __forceinline__ void mid(f32x4 (&acc)[2][2][4][2], const Unit& u, int wr, int wc, int fr, int fq, bool second) const {
;     ...
;         const int on = second ? 2048 : 0, od = second ? 4096 : 2048;
;         const float nfloor = second ? 1e-20f : 0.f;
;         u32x4 gn[2][2], gd[2][2];
; #pragma unroll
;         for (int bj = 0; bj < 2; ++bj) { gn[0][bj] = *(const u32x4*)(GT + r0 * ldg + on + col0 + bj * HALF); gd[0][bj] = *(const u32x4*)(GT + r0 * ldg + od + col0 + bj * HALF); }
; #pragma unroll
;         for (int gi = 0; gi < 8; ++gi) {
;             const int ai = gi >> 2, m = gi & 3;
;             if (gi < 7) { const size_t row2 = r0 + ((gi + 1) >> 2) * HALF + ((gi + 1) & 3) * 16;
; #pragma unroll
;                 for (int bj = 0; bj < 2; ++bj) { gn[(gi + 1) & 1][bj] = *(const u32x4*)(GT + row2 * ldg + on + col0 + bj * HALF); gd[(gi + 1) & 1][bj] = *(const u32x4*)(GT + row2 * ldg + od + col0 + bj * HALF); } }
;             asm volatile("" ::: "memory");
; #pragma unroll
;             for (int bj = 0; bj < 2; ++bj) {
;                 f32x4 n0, n1, d0, d1; unpack(gn[gi & 1][bj], n0, n1); unpack(gd[gi & 1][bj], d0, d1);
; #pragma unroll
;                 for (int j = 0; j < 4; ++j) {
;                     acc[ai][bj][m][0][j] *= fmaxf(n0[j], nfloor) * __builtin_amdgcn_rcpf(fmaxf(d0[j], 1e-20f));
;                     acc[ai][bj][m][1][j] *= fmaxf(n1[j], nfloor) * __builtin_amdgcn_rcpf(fmaxf(d1[j], 1e-20f)); }
;             }
.LBB0_992:
	s_andn2_b64 vcc, exec, s[28:29]
	s_cbranch_vccnz .LBB0_994
	s_cmp_eq_u32 s62, 32
	s_cselect_b64 vcc, -1, 0
	s_and_b64 s[28:29], vcc, exec
	s_cselect_b32 s66, 0x1000, 0
	v_lshl_add_u64 v[4:5], v[188:189], 0, s[66:67]
	global_load_dwordx4 v[158:161], v[4:5], off
	s_mov_b32 s29, s67
	s_cselect_b32 s28, s71, 0x1000
	v_lshl_add_u64 v[134:135], v[188:189], 0, s[28:29]
	global_load_dwordx4 v[162:165], v[134:135], off
	global_load_dwordx4 v[154:157], v[4:5], off offset:256
	global_load_dwordx4 v[150:153], v[134:135], off offset:256
	v_lshl_add_u64 v[4:5], v[190:191], 0, s[66:67]
	v_lshl_add_u64 v[134:135], v[190:191], 0, s[28:29]
	global_load_dwordx4 v[146:149], v[4:5], off
	global_load_dwordx4 v[138:141], v[4:5], off offset:256
	global_load_dwordx4 v[142:145], v[134:135], off
	s_nop 0
	global_load_dwordx4 v[134:137], v[134:135], off offset:256
	v_mov_b32_e32 v3, 0x1e3ce508
	v_cndmask_b32_e32 v3, 0, v3, vcc
	s_waitcnt vmcnt(7)
	v_lshlrev_b32_e32 v4, 16, v158
	v_and_b32_e32 v5, 0xffff0000, v158
	v_lshlrev_b32_e32 v158, 16, v159
	v_lshlrev_b32_e32 v166, 16, v160
	v_lshlrev_b32_e32 v167, 16, v161
	s_waitcnt vmcnt(6)
	v_lshlrev_b32_e32 v168, 16, v162
	v_and_b32_e32 v162, 0xffff0000, v162
	v_lshlrev_b32_e32 v169, 16, v163
	v_and_b32_e32 v163, 0xffff0000, v163
	v_lshlrev_b32_e32 v170, 16, v164
	v_and_b32_e32 v164, 0xffff0000, v164
	v_lshlrev_b32_e32 v171, 16, v165
	v_and_b32_e32 v165, 0xffff0000, v165
	s_waitcnt vmcnt(5)
	v_lshlrev_b32_e32 v185, 16, v155
	v_and_b32_e32 v187, 0xffff0000, v155
	v_lshlrev_b32_e32 v192, 16, v156
	v_and_b32_e32 v193, 0xffff0000, v156
	v_lshlrev_b32_e32 v196, 16, v157
	v_and_b32_e32 v197, 0xffff0000, v157
	v_max_f32_e32 v155, v166, v166
	v_max_f32_e32 v157, v162, v162
	v_max_f32_e32 v162, v164, v164
	v_max_f32_e32 v164, v169, v169
	v_max_f32_e32 v166, v167, v167
	v_max_f32_e32 v167, v171, v171
	v_and_b32_e32 v159, 0xffff0000, v159
	v_and_b32_e32 v160, 0xffff0000, v160
	v_and_b32_e32 v161, 0xffff0000, v161
	v_lshlrev_b32_e32 v172, 16, v154
	v_and_b32_e32 v173, 0xffff0000, v154
	v_max_f32_e32 v169, 0x1e3ce508, v170
	v_max_f32_e32 v171, 0x1e3ce508, v162
	v_max_f32_e32 v156, v158, v3
	v_max_f32_e32 v164, 0x1e3ce508, v164
	v_max_f32_e32 v158, v166, v3
	v_max_f32_e32 v166, 0x1e3ce508, v167
	v_max_f32_e32 v167, 0x1e3ce508, v163
	v_max_f32_e32 v199, 0x1e3ce508, v165
	v_max_f32_e32 v168, 0x1e3ce508, v168
	v_max_f32_e32 v170, 0x1e3ce508, v157
	v_rcp_f32_e32 v162, v169
	v_rcp_f32_e32 v163, v171
	v_rcp_f32_e32 v164, v164
	v_rcp_f32_e32 v165, v167
	v_rcp_f32_e32 v166, v166
	v_rcp_f32_e32 v167, v199
	v_max_f32_e32 v154, v155, v3
	v_max_f32_e32 v155, v160, v3
	v_max_f32_e32 v157, v159, v3
	v_max_f32_e32 v159, v161, v3
	v_rcp_f32_e32 v160, v168
	v_rcp_f32_e32 v161, v170
	v_max_f32_e32 v4, v4, v4
	v_max_f32_e32 v5, v5, v5
	v_max_f32_e32 v4, v4, v3
	v_max_f32_e32 v5, v5, v3
	v_pk_mul_f32 v[156:157], v[156:157], v[164:165]
	v_pk_mul_f32 v[154:155], v[154:155], v[162:163]
	v_pk_mul_f32 v[158:159], v[158:159], v[166:167]
	s_waitcnt vmcnt(4)
	v_lshlrev_b32_e32 v198, 16, v150
	v_pk_mul_f32 v[4:5], v[4:5], v[160:161]
	v_pk_mul_f32 v[128:129], v[128:129], v[156:157]
	v_pk_mul_f32 v[132:133], v[132:133], v[158:159]
	v_pk_mul_f32 v[130:131], v[130:131], v[154:155]
	v_and_b32_e32 v155, 0xffff0000, v150
	v_lshlrev_b32_e32 v157, 16, v151
	v_and_b32_e32 v159, 0xffff0000, v151
	v_pk_mul_f32 v[126:127], v[126:127], v[4:5]
	v_lshlrev_b32_e32 v5, 16, v152
	v_and_b32_e32 v156, 0xffff0000, v152
	v_max_f32_e32 v152, v192, v3
	v_max_f32_e32 v150, 0x1e3ce508, v198
	v_max_f32_e32 v151, 0x1e3ce508, v155
	v_rcp_f32_e32 v150, v150
	v_max_f32_e32 v5, v5, v5
	v_rcp_f32_e32 v151, v151
	v_max_f32_e32 v157, 0x1e3ce508, v157
	v_lshlrev_b32_e32 v161, 16, v153
	v_max_f32_e32 v5, 0x1e3ce508, v5
	v_rcp_f32_e32 v158, v157
	v_max_f32_e32 v157, v196, v196
	v_max_f32_e32 v4, v172, v172
	v_rcp_f32_e32 v154, v5
	v_max_f32_e32 v5, v173, v173
	v_max_f32_e32 v160, v157, v3
	v_max_f32_e32 v157, v161, v161
	v_max_f32_e32 v4, v4, v3
	v_max_f32_e32 v5, v5, v3
	v_max_f32_e32 v157, 0x1e3ce508, v157
	v_and_b32_e32 v163, 0xffff0000, v153
	v_rcp_f32_e32 v162, v157
	v_max_f32_e32 v157, v159, v159
	v_pk_mul_f32 v[4:5], v[4:5], v[150:151]
	v_max_f32_e32 v155, v156, v156
	v_max_f32_e32 v157, 0x1e3ce508, v157
	v_pk_mul_f32 v[122:123], v[122:123], v[4:5]
	v_max_f32_e32 v155, 0x1e3ce508, v155
	v_rcp_f32_e32 v159, v157
	v_max_f32_e32 v4, 0x1e3ce508, v163
	v_rcp_f32_e32 v155, v155
	v_rcp_f32_e32 v163, v4
	v_max_f32_e32 v156, v185, v185
	v_max_f32_e32 v157, v187, v187
	v_max_f32_e32 v153, v193, v193
	v_max_f32_e32 v156, v156, v3
	v_max_f32_e32 v157, v157, v3
	v_max_f32_e32 v153, v153, v3
	v_pk_mul_f32 v[150:151], v[156:157], v[158:159]
	v_max_f32_e32 v161, v197, v3
	v_pk_mul_f32 v[124:125], v[124:125], v[150:151]
	v_pk_mul_f32 v[4:5], v[152:153], v[154:155]
	v_pk_mul_f32 v[150:151], v[160:161], v[162:163]
	v_pk_mul_f32 v[118:119], v[118:119], v[4:5]
	v_pk_mul_f32 v[120:121], v[120:121], v[150:151]
	v_lshl_add_u64 v[4:5], v[204:205], 0, s[66:67]
	v_lshl_add_u64 v[150:151], v[204:205], 0, s[28:29]
	global_load_dwordx4 v[166:169], v[4:5], off
	global_load_dwordx4 v[154:157], v[4:5], off offset:256
	global_load_dwordx4 v[158:161], v[150:151], off
	s_nop 0
	global_load_dwordx4 v[150:153], v[150:151], off offset:256
	s_waitcnt vmcnt(5)
;     static __device__ __forceinline__ void unpack(const u32x4 g4, f32x4& g0, f32x4& g1) { g0 = (f32x4){bflo(g4.x), bfhi(g4.x), bflo(g4.y), bfhi(g4.y)}; g1 = (f32x4){bflo(g4.z), bfhi(g4.z), bflo(g4.w), bfhi(g4.w)}; }
;     __device__ __forceinline__ void mid(f32x4 (&acc)[2][2][4][2], const Unit& u, int wr, int wc, int fr, int fq, bool second) const {
;     ...
;         for (int gi = 0; gi < 8; ++gi) {
;             const int ai = gi >> 2, m = gi & 3;
;             if (gi < 7) { const size_t row2 = r0 + ((gi + 1) >> 2) * HALF + ((gi + 1) & 3) * 16;
; #pragma unroll
;                 for (int bj = 0; bj < 2; ++bj) { gn[(gi + 1) & 1][bj] = *(const u32x4*)(GT + row2 * ldg + on + col0 + bj * HALF); gd[(gi + 1) & 1][bj] = *(const u32x4*)(GT + row2 * ldg + od + col0 + bj * HALF); } }
;             asm volatile("" ::: "memory");
; #pragma unroll
;             for (int bj = 0; bj < 2; ++bj) {
;                 f32x4 n0, n1, d0, d1; unpack(gn[gi & 1][bj], n0, n1); unpack(gd[gi & 1][bj], d0, d1);
; #pragma unroll
;                 for (int j = 0; j < 4; ++j) {
;                     acc[ai][bj][m][0][j] *= fmaxf(n0[j], nfloor) * __builtin_amdgcn_rcpf(fmaxf(d0[j], 1e-20f));
;                     acc[ai][bj][m][1][j] *= fmaxf(n1[j], nfloor) * __builtin_amdgcn_rcpf(fmaxf(d1[j], 1e-20f)); }
;             }
	v_lshlrev_b32_e32 v164, 16, v143
	v_and_b32_e32 v171, 0xffff0000, v143
	v_lshlrev_b32_e32 v143, 16, v144
	v_lshlrev_b32_e32 v4, 16, v146
	v_and_b32_e32 v5, 0xffff0000, v146
	v_lshlrev_b32_e32 v162, 16, v147
	v_and_b32_e32 v165, 0xffff0000, v147
	v_lshlrev_b32_e32 v146, 16, v148
	v_and_b32_e32 v147, 0xffff0000, v148
	v_lshlrev_b32_e32 v163, 16, v149
	v_and_b32_e32 v172, 0xffff0000, v149
	v_lshlrev_b32_e32 v148, 16, v142
	v_and_b32_e32 v149, 0xffff0000, v142
	v_max_f32_e32 v143, 0x1e3ce508, v143
	v_and_b32_e32 v170, 0xffff0000, v144
	v_max_f32_e32 v144, v146, v146
	v_rcp_f32_e32 v146, v143
	v_max_f32_e32 v143, v149, v149
	v_max_f32_e32 v142, 0x1e3ce508, v148
	v_max_f32_e32 v143, 0x1e3ce508, v143
	v_max_f32_e32 v149, v164, v164
	v_rcp_f32_e32 v142, v142
	v_rcp_f32_e32 v143, v143
	v_max_f32_e32 v149, 0x1e3ce508, v149
	v_lshlrev_b32_e32 v173, 16, v145
	v_max_f32_e32 v148, v162, v162
	v_rcp_f32_e32 v162, v149
	v_max_f32_e32 v149, v163, v163
	v_max_f32_e32 v4, v4, v4
	v_max_f32_e32 v5, v5, v5
	v_max_f32_e32 v164, v149, v3
	v_max_f32_e32 v149, v173, v173
	v_max_f32_e32 v4, v4, v3
	v_max_f32_e32 v5, v5, v3
	v_max_f32_e32 v149, 0x1e3ce508, v149
	v_and_b32_e32 v185, 0xffff0000, v145
	v_max_f32_e32 v145, v147, v147
	v_max_f32_e32 v147, v170, v170
	v_rcp_f32_e32 v170, v149
	v_max_f32_e32 v149, v171, v171
	v_pk_mul_f32 v[4:5], v[4:5], v[142:143]
	v_max_f32_e32 v147, 0x1e3ce508, v147
	v_max_f32_e32 v149, 0x1e3ce508, v149
	v_pk_mul_f32 v[114:115], v[114:115], v[4:5]
	v_rcp_f32_e32 v147, v147
	v_rcp_f32_e32 v163, v149
	v_max_f32_e32 v4, 0x1e3ce508, v185
	v_rcp_f32_e32 v171, v4
	v_max_f32_e32 v149, v165, v165
	v_max_f32_e32 v144, v144, v3
	v_max_f32_e32 v145, v145, v3
	v_max_f32_e32 v148, v148, v3
	v_max_f32_e32 v149, v149, v3
	v_pk_mul_f32 v[142:143], v[148:149], v[162:163]
	v_max_f32_e32 v165, v172, v3
	v_pk_mul_f32 v[4:5], v[144:145], v[146:147]
	s_waitcnt vmcnt(4)
	v_lshlrev_b32_e32 v144, 16, v135
	v_and_b32_e32 v147, 0xffff0000, v135
	v_lshlrev_b32_e32 v135, 16, v136
	v_pk_mul_f32 v[116:117], v[116:117], v[142:143]
	v_pk_mul_f32 v[142:143], v[164:165], v[170:171]
	v_pk_mul_f32 v[112:113], v[112:113], v[142:143]
	v_pk_mul_f32 v[110:111], v[110:111], v[4:5]
	v_lshlrev_b32_e32 v4, 16, v138
	v_and_b32_e32 v5, 0xffff0000, v138
	v_lshlrev_b32_e32 v142, 16, v139
	v_and_b32_e32 v145, 0xffff0000, v139
	v_lshlrev_b32_e32 v138, 16, v140
	v_and_b32_e32 v139, 0xffff0000, v140
	v_lshlrev_b32_e32 v143, 16, v141
	v_and_b32_e32 v148, 0xffff0000, v141
	v_lshlrev_b32_e32 v140, 16, v134
	v_and_b32_e32 v141, 0xffff0000, v134
	v_max_f32_e32 v135, 0x1e3ce508, v135
	v_and_b32_e32 v146, 0xffff0000, v136
	v_max_f32_e32 v136, v138, v138
	v_rcp_f32_e32 v138, v135
	v_max_f32_e32 v135, v141, v141
	v_max_f32_e32 v134, 0x1e3ce508, v140
	v_max_f32_e32 v135, 0x1e3ce508, v135
	v_max_f32_e32 v141, v144, v144
	v_rcp_f32_e32 v134, v134
	v_rcp_f32_e32 v135, v135
	v_max_f32_e32 v141, 0x1e3ce508, v141
	v_lshlrev_b32_e32 v149, 16, v137
	v_max_f32_e32 v140, v142, v142
	v_rcp_f32_e32 v142, v141
	v_max_f32_e32 v141, v143, v143
	v_max_f32_e32 v4, v4, v4
	v_max_f32_e32 v5, v5, v5
	v_max_f32_e32 v144, v141, v3
	v_max_f32_e32 v141, v149, v149
	v_max_f32_e32 v4, v4, v3
	v_max_f32_e32 v5, v5, v3
	v_max_f32_e32 v141, 0x1e3ce508, v141
	v_and_b32_e32 v162, 0xffff0000, v137
	v_max_f32_e32 v137, v139, v139
	v_max_f32_e32 v139, v146, v146
	v_rcp_f32_e32 v146, v141
	v_max_f32_e32 v141, v147, v147
	v_pk_mul_f32 v[4:5], v[4:5], v[134:135]
	v_max_f32_e32 v141, 0x1e3ce508, v141
	v_pk_mul_f32 v[106:107], v[106:107], v[4:5]
	v_max_f32_e32 v4, v162, v162
	v_max_f32_e32 v139, 0x1e3ce508, v139
	v_rcp_f32_e32 v143, v141
	v_max_f32_e32 v4, 0x1e3ce508, v4
	v_rcp_f32_e32 v139, v139
	v_rcp_f32_e32 v147, v4
	v_max_f32_e32 v141, v145, v145
	v_max_f32_e32 v140, v140, v3
	v_max_f32_e32 v141, v141, v3
	v_max_f32_e32 v4, v148, v148
	v_max_f32_e32 v136, v136, v3
	v_max_f32_e32 v137, v137, v3
	v_pk_mul_f32 v[134:135], v[140:141], v[142:143]
	v_max_f32_e32 v145, v4, v3
	v_pk_mul_f32 v[108:109], v[108:109], v[134:135]
	v_pk_mul_f32 v[4:5], v[136:137], v[138:139]
	v_pk_mul_f32 v[134:135], v[144:145], v[146:147]
	v_pk_mul_f32 v[102:103], v[102:103], v[4:5]
	v_pk_mul_f32 v[104:105], v[104:105], v[134:135]
	v_lshl_add_u64 v[4:5], v[206:207], 0, s[66:67]
	v_lshl_add_u64 v[134:135], v[206:207], 0, s[28:29]
	global_load_dwordx4 v[170:173], v[4:5], off
	global_load_dwordx4 v[142:145], v[4:5], off offset:256
	global_load_dwordx4 v[162:165], v[134:135], off
	s_nop 0
	global_load_dwordx4 v[134:137], v[134:135], off offset:256
	s_waitcnt vmcnt(7)
	v_lshlrev_b32_e32 v139, 16, v168
	s_waitcnt vmcnt(5)
	v_lshlrev_b32_e32 v146, 16, v160
	v_max_f32_e32 v140, v139, v3
	v_lshlrev_b32_e32 v138, 16, v158
	v_and_b32_e32 v147, 0xffff0000, v158
	v_max_f32_e32 v139, 0x1e3ce508, v146
	v_rcp_f32_e32 v146, v139
	v_max_f32_e32 v139, v147, v147
	v_max_f32_e32 v138, 0x1e3ce508, v138
	v_max_f32_e32 v139, 0x1e3ce508, v139
	v_rcp_f32_e32 v138, v138
	v_rcp_f32_e32 v139, v139
	v_lshlrev_b32_e32 v4, 16, v166
	v_and_b32_e32 v5, 0xffff0000, v166
	v_max_f32_e32 v4, v4, v4
	v_max_f32_e32 v5, v5, v5
	v_lshlrev_b32_e32 v158, 16, v159
	v_and_b32_e32 v159, 0xffff0000, v159
	v_max_f32_e32 v4, v4, v3
	v_max_f32_e32 v5, v5, v3
	v_lshlrev_b32_e32 v148, 16, v167
	v_and_b32_e32 v149, 0xffff0000, v167
	v_lshlrev_b32_e32 v166, 16, v169
	v_and_b32_e32 v160, 0xffff0000, v160
	v_lshlrev_b32_e32 v167, 16, v161
	v_and_b32_e32 v161, 0xffff0000, v161
	v_pk_mul_f32 v[4:5], v[4:5], v[138:139]
	v_max_f32_e32 v147, v160, v160
	v_max_f32_e32 v158, 0x1e3ce508, v158
	v_max_f32_e32 v160, v166, v166
	v_max_f32_e32 v159, 0x1e3ce508, v159
	v_pk_mul_f32 v[98:99], v[98:99], v[4:5]
	v_rcp_f32_e32 v158, v158
	v_max_f32_e32 v166, 0x1e3ce508, v167
	v_rcp_f32_e32 v159, v159
	v_max_f32_e32 v4, 0x1e3ce508, v161
	v_rcp_f32_e32 v166, v166
	v_rcp_f32_e32 v167, v4
	v_and_b32_e32 v141, 0xffff0000, v168
	v_and_b32_e32 v168, 0xffff0000, v169
	v_max_f32_e32 v147, 0x1e3ce508, v147
	v_max_f32_e32 v148, v148, v148
	v_max_f32_e32 v149, v149, v149
	v_rcp_f32_e32 v147, v147
	v_max_f32_e32 v148, v148, v3
	v_max_f32_e32 v149, v149, v3
	v_max_f32_e32 v4, v168, v168
	v_max_f32_e32 v160, v160, v3
	v_pk_mul_f32 v[138:139], v[148:149], v[158:159]
	v_max_f32_e32 v161, v4, v3
	v_pk_mul_f32 v[100:101], v[100:101], v[138:139]
	v_pk_mul_f32 v[138:139], v[160:161], v[166:167]
	v_max_f32_e32 v141, v141, v3
	v_pk_mul_f32 v[96:97], v[96:97], v[138:139]
	v_lshlrev_b32_e32 v139, 16, v156
	v_pk_mul_f32 v[4:5], v[140:141], v[146:147]
	s_waitcnt vmcnt(4)
;     static __device__ __forceinline__ void unpack(const u32x4 g4, f32x4& g0, f32x4& g1) { g0 = (f32x4){bflo(g4.x), bfhi(g4.x), bflo(g4.y), bfhi(g4.y)}; g1 = (f32x4){bflo(g4.z), bfhi(g4.z), bflo(g4.w), bfhi(g4.w)}; }
;     __device__ __forceinline__ void mid(f32x4 (&acc)[2][2][4][2], const Unit& u, int wr, int wc, int fr, int fq, bool second) const {
;     ...
;         for (int gi = 0; gi < 8; ++gi) {
;             const int ai = gi >> 2, m = gi & 3;
;             if (gi < 7) { const size_t row2 = r0 + ((gi + 1) >> 2) * HALF + ((gi + 1) & 3) * 16;
; #pragma unroll
;                 for (int bj = 0; bj < 2; ++bj) { gn[(gi + 1) & 1][bj] = *(const u32x4*)(GT + row2 * ldg + on + col0 + bj * HALF); gd[(gi + 1) & 1][bj] = *(const u32x4*)(GT + row2 * ldg + od + col0 + bj * HALF); } }
;             asm volatile("" ::: "memory");
; #pragma unroll
;             for (int bj = 0; bj < 2; ++bj) {
;                 f32x4 n0, n1, d0, d1; unpack(gn[gi & 1][bj], n0, n1); unpack(gd[gi & 1][bj], d0, d1);
; #pragma unroll
;                 for (int j = 0; j < 4; ++j) {
;                     acc[ai][bj][m][0][j] *= fmaxf(n0[j], nfloor) * __builtin_amdgcn_rcpf(fmaxf(d0[j], 1e-20f));
;                     acc[ai][bj][m][1][j] *= fmaxf(n1[j], nfloor) * __builtin_amdgcn_rcpf(fmaxf(d1[j], 1e-20f)); }
;             }
	v_lshlrev_b32_e32 v146, 16, v152
	v_max_f32_e32 v140, v139, v3
	v_lshlrev_b32_e32 v138, 16, v150
	v_and_b32_e32 v147, 0xffff0000, v150
	v_max_f32_e32 v139, 0x1e3ce508, v146
	v_rcp_f32_e32 v146, v139
	v_max_f32_e32 v139, v147, v147
	v_max_f32_e32 v138, 0x1e3ce508, v138
	v_max_f32_e32 v139, 0x1e3ce508, v139
	v_rcp_f32_e32 v138, v138
	v_rcp_f32_e32 v139, v139
	v_pk_mul_f32 v[94:95], v[94:95], v[4:5]
	v_lshlrev_b32_e32 v4, 16, v154
	v_and_b32_e32 v5, 0xffff0000, v154
	v_max_f32_e32 v4, v4, v4
	v_max_f32_e32 v5, v5, v5
	v_lshlrev_b32_e32 v150, 16, v151
	v_and_b32_e32 v151, 0xffff0000, v151
	v_max_f32_e32 v4, v4, v3
	v_max_f32_e32 v5, v5, v3
	v_lshlrev_b32_e32 v148, 16, v155
	v_and_b32_e32 v149, 0xffff0000, v155
	v_lshlrev_b32_e32 v154, 16, v157
	v_and_b32_e32 v152, 0xffff0000, v152
	v_lshlrev_b32_e32 v155, 16, v153
	v_and_b32_e32 v153, 0xffff0000, v153
	v_pk_mul_f32 v[4:5], v[4:5], v[138:139]
	v_max_f32_e32 v147, v152, v152
	v_max_f32_e32 v150, 0x1e3ce508, v150
	v_max_f32_e32 v152, v154, v154
	v_max_f32_e32 v151, 0x1e3ce508, v151
	v_pk_mul_f32 v[90:91], v[90:91], v[4:5]
	v_max_f32_e32 v147, 0x1e3ce508, v147
	v_rcp_f32_e32 v150, v150
	v_max_f32_e32 v154, 0x1e3ce508, v155
	v_rcp_f32_e32 v151, v151
	v_max_f32_e32 v4, 0x1e3ce508, v153
	v_rcp_f32_e32 v147, v147
	v_rcp_f32_e32 v154, v154
	v_rcp_f32_e32 v155, v4
	v_and_b32_e32 v141, 0xffff0000, v156
	v_and_b32_e32 v156, 0xffff0000, v157
	v_max_f32_e32 v148, v148, v148
	v_max_f32_e32 v149, v149, v149
	v_max_f32_e32 v141, v141, v141
	v_max_f32_e32 v148, v148, v3
	v_max_f32_e32 v149, v149, v3
	v_max_f32_e32 v141, v141, v3
	v_max_f32_e32 v152, v152, v3
	v_pk_mul_f32 v[138:139], v[148:149], v[150:151]
	v_max_f32_e32 v153, v156, v3
	v_pk_mul_f32 v[92:93], v[92:93], v[138:139]
	v_pk_mul_f32 v[4:5], v[140:141], v[146:147]
	v_pk_mul_f32 v[138:139], v[152:153], v[154:155]
	v_pk_mul_f32 v[86:87], v[86:87], v[4:5]
	v_pk_mul_f32 v[88:89], v[88:89], v[138:139]
	v_lshl_add_u64 v[4:5], v[208:209], 0, s[66:67]
	v_lshl_add_u64 v[138:139], v[208:209], 0, s[28:29]
	s_waitcnt vmcnt(3)
	v_lshlrev_b32_e32 v155, 16, v172
	global_load_dwordx4 v[158:161], v[4:5], off
	global_load_dwordx4 v[146:149], v[4:5], off offset:256
	global_load_dwordx4 v[150:153], v[138:139], off
	s_nop 0
	global_load_dwordx4 v[138:141], v[138:139], off offset:256
	s_waitcnt vmcnt(5)
	v_lshlrev_b32_e32 v154, 16, v162
	v_and_b32_e32 v168, 0xffff0000, v162
	v_lshlrev_b32_e32 v162, 16, v164
	v_max_f32_e32 v156, v155, v3
	v_max_f32_e32 v155, 0x1e3ce508, v162
	v_lshlrev_b32_e32 v4, 16, v170
	v_and_b32_e32 v5, 0xffff0000, v170
	v_lshlrev_b32_e32 v170, 16, v163
	v_rcp_f32_e32 v162, v155
	v_max_f32_e32 v155, v168, v168
	v_and_b32_e32 v157, 0xffff0000, v172
	v_lshlrev_b32_e32 v167, 16, v173
	v_and_b32_e32 v172, 0xffff0000, v173
	v_lshlrev_b32_e32 v173, 16, v165
	v_and_b32_e32 v185, 0xffff0000, v165
	v_max_f32_e32 v154, 0x1e3ce508, v154
	v_max_f32_e32 v155, 0x1e3ce508, v155
	v_lshlrev_b32_e32 v166, 16, v171
	v_rcp_f32_e32 v154, v154
	v_rcp_f32_e32 v155, v155
	v_max_f32_e32 v165, 0x1e3ce508, v170
	v_and_b32_e32 v169, 0xffff0000, v171
	v_and_b32_e32 v171, 0xffff0000, v163
	v_and_b32_e32 v163, 0xffff0000, v164
	v_max_f32_e32 v164, v166, v166
	v_rcp_f32_e32 v166, v165
	v_max_f32_e32 v165, v167, v167
	v_max_f32_e32 v4, v4, v4
	v_max_f32_e32 v5, v5, v5
	v_max_f32_e32 v168, v165, v3
	v_max_f32_e32 v165, v173, v173
	v_max_f32_e32 v4, v4, v3
	v_max_f32_e32 v5, v5, v3
	v_max_f32_e32 v165, 0x1e3ce508, v165
	v_rcp_f32_e32 v170, v165
	v_max_f32_e32 v165, v171, v171
	v_pk_mul_f32 v[4:5], v[4:5], v[154:155]
	v_max_f32_e32 v163, 0x1e3ce508, v163
	v_max_f32_e32 v165, 0x1e3ce508, v165
	v_pk_mul_f32 v[82:83], v[82:83], v[4:5]
	v_rcp_f32_e32 v163, v163
	v_rcp_f32_e32 v167, v165
	v_max_f32_e32 v4, 0x1e3ce508, v185
	v_rcp_f32_e32 v171, v4
	v_max_f32_e32 v157, v157, v157
	v_max_f32_e32 v165, v169, v169
	v_max_f32_e32 v157, v157, v3
	v_max_f32_e32 v164, v164, v3
	v_max_f32_e32 v165, v165, v3
	v_pk_mul_f32 v[154:155], v[164:165], v[166:167]
	v_max_f32_e32 v169, v172, v3
	v_pk_mul_f32 v[4:5], v[156:157], v[162:163]
	s_waitcnt vmcnt(4)
	v_lshlrev_b32_e32 v156, 16, v135
	v_and_b32_e32 v163, 0xffff0000, v135
	v_lshlrev_b32_e32 v135, 16, v136
	v_pk_mul_f32 v[84:85], v[84:85], v[154:155]
	v_pk_mul_f32 v[154:155], v[168:169], v[170:171]
	v_pk_mul_f32 v[80:81], v[80:81], v[154:155]
	v_pk_mul_f32 v[78:79], v[78:79], v[4:5]
	v_lshlrev_b32_e32 v4, 16, v142
	v_and_b32_e32 v5, 0xffff0000, v142
	v_lshlrev_b32_e32 v154, 16, v143
	v_and_b32_e32 v157, 0xffff0000, v143
	v_lshlrev_b32_e32 v142, 16, v144
	v_and_b32_e32 v143, 0xffff0000, v144
	v_lshlrev_b32_e32 v155, 16, v145
	v_and_b32_e32 v164, 0xffff0000, v145
	v_lshlrev_b32_e32 v144, 16, v134
	v_and_b32_e32 v145, 0xffff0000, v134
	v_max_f32_e32 v135, 0x1e3ce508, v135
	v_and_b32_e32 v162, 0xffff0000, v136
	v_max_f32_e32 v136, v142, v142
	v_rcp_f32_e32 v142, v135
	v_max_f32_e32 v135, v145, v145
	v_max_f32_e32 v134, 0x1e3ce508, v144
	v_max_f32_e32 v135, 0x1e3ce508, v135
	v_max_f32_e32 v145, v156, v156
	v_rcp_f32_e32 v134, v134
	v_rcp_f32_e32 v135, v135
	v_max_f32_e32 v145, 0x1e3ce508, v145
	v_lshlrev_b32_e32 v165, 16, v137
	v_max_f32_e32 v144, v154, v154
	v_rcp_f32_e32 v154, v145
	v_max_f32_e32 v145, v155, v155
	v_max_f32_e32 v4, v4, v4
	v_max_f32_e32 v5, v5, v5
	v_max_f32_e32 v156, v145, v3
	v_max_f32_e32 v145, v165, v165
	v_max_f32_e32 v4, v4, v3
	v_max_f32_e32 v5, v5, v3
	v_max_f32_e32 v145, 0x1e3ce508, v145
	v_and_b32_e32 v166, 0xffff0000, v137
	v_max_f32_e32 v137, v143, v143
	v_max_f32_e32 v143, v162, v162
	v_rcp_f32_e32 v162, v145
	v_max_f32_e32 v145, v163, v163
	v_pk_mul_f32 v[4:5], v[4:5], v[134:135]
	v_max_f32_e32 v145, 0x1e3ce508, v145
	v_pk_mul_f32 v[74:75], v[74:75], v[4:5]
	v_max_f32_e32 v4, v166, v166
	v_max_f32_e32 v143, 0x1e3ce508, v143
	v_rcp_f32_e32 v155, v145
	v_max_f32_e32 v4, 0x1e3ce508, v4
	v_rcp_f32_e32 v143, v143
	v_rcp_f32_e32 v163, v4
	v_max_f32_e32 v145, v157, v157
	v_max_f32_e32 v144, v144, v3
	v_max_f32_e32 v145, v145, v3
	v_max_f32_e32 v4, v164, v164
	v_max_f32_e32 v136, v136, v3
	v_max_f32_e32 v137, v137, v3
	v_pk_mul_f32 v[134:135], v[144:145], v[154:155]
	v_max_f32_e32 v157, v4, v3
	v_pk_mul_f32 v[76:77], v[76:77], v[134:135]
	v_pk_mul_f32 v[4:5], v[136:137], v[142:143]
	v_pk_mul_f32 v[134:135], v[156:157], v[162:163]
	v_pk_mul_f32 v[70:71], v[70:71], v[4:5]
	v_pk_mul_f32 v[72:73], v[72:73], v[134:135]
	v_lshl_add_u64 v[4:5], v[210:211], 0, s[66:67]
	v_lshl_add_u64 v[134:135], v[210:211], 0, s[28:29]
	global_load_dwordx4 v[162:165], v[4:5], off
	global_load_dwordx4 v[142:145], v[4:5], off offset:256
	global_load_dwordx4 v[154:157], v[134:135], off
	s_nop 0
	global_load_dwordx4 v[134:137], v[134:135], off offset:256
	s_waitcnt vmcnt(5)
;     static __device__ __forceinline__ void unpack(const u32x4 g4, f32x4& g0, f32x4& g1) { g0 = (f32x4){bflo(g4.x), bfhi(g4.x), bflo(g4.y), bfhi(g4.y)}; g1 = (f32x4){bflo(g4.z), bfhi(g4.z), bflo(g4.w), bfhi(g4.w)}; }
;     __device__ __forceinline__ void mid(f32x4 (&acc)[2][2][4][2], const Unit& u, int wr, int wc, int fr, int fq, bool second) const {
;     ...
;         for (int gi = 0; gi < 8; ++gi) {
;             const int ai = gi >> 2, m = gi & 3;
;             if (gi < 7) { const size_t row2 = r0 + ((gi + 1) >> 2) * HALF + ((gi + 1) & 3) * 16;
; #pragma unroll
;                 for (int bj = 0; bj < 2; ++bj) { gn[(gi + 1) & 1][bj] = *(const u32x4*)(GT + row2 * ldg + on + col0 + bj * HALF); gd[(gi + 1) & 1][bj] = *(const u32x4*)(GT + row2 * ldg + od + col0 + bj * HALF); } }
;             asm volatile("" ::: "memory");
; #pragma unroll
;             for (int bj = 0; bj < 2; ++bj) {
;                 f32x4 n0, n1, d0, d1; unpack(gn[gi & 1][bj], n0, n1); unpack(gd[gi & 1][bj], d0, d1);
; #pragma unroll
;                 for (int j = 0; j < 4; ++j) {
;                     acc[ai][bj][m][0][j] *= fmaxf(n0[j], nfloor) * __builtin_amdgcn_rcpf(fmaxf(d0[j], 1e-20f));
;                     acc[ai][bj][m][1][j] *= fmaxf(n1[j], nfloor) * __builtin_amdgcn_rcpf(fmaxf(d1[j], 1e-20f)); }
;             }
	v_lshlrev_b32_e32 v168, 16, v151
	v_and_b32_e32 v171, 0xffff0000, v151
	v_lshlrev_b32_e32 v151, 16, v152
	v_lshlrev_b32_e32 v4, 16, v158
	v_and_b32_e32 v5, 0xffff0000, v158
	v_lshlrev_b32_e32 v166, 16, v159
	v_and_b32_e32 v169, 0xffff0000, v159
	v_lshlrev_b32_e32 v158, 16, v160
	v_and_b32_e32 v159, 0xffff0000, v160
	v_lshlrev_b32_e32 v167, 16, v161
	v_and_b32_e32 v172, 0xffff0000, v161
	v_lshlrev_b32_e32 v160, 16, v150
	v_and_b32_e32 v161, 0xffff0000, v150
	v_max_f32_e32 v151, 0x1e3ce508, v151
	v_and_b32_e32 v170, 0xffff0000, v152
	v_max_f32_e32 v152, v158, v158
	v_rcp_f32_e32 v158, v151
	v_max_f32_e32 v151, v161, v161
	v_max_f32_e32 v150, 0x1e3ce508, v160
	v_max_f32_e32 v151, 0x1e3ce508, v151
	v_max_f32_e32 v161, v168, v168
	v_rcp_f32_e32 v150, v150
	v_rcp_f32_e32 v151, v151
	v_max_f32_e32 v161, 0x1e3ce508, v161
	v_lshlrev_b32_e32 v173, 16, v153
	v_max_f32_e32 v160, v166, v166
	v_rcp_f32_e32 v166, v161
	v_max_f32_e32 v161, v167, v167
	v_max_f32_e32 v4, v4, v4
	v_max_f32_e32 v5, v5, v5
	v_max_f32_e32 v168, v161, v3
	v_max_f32_e32 v161, v173, v173
	v_max_f32_e32 v4, v4, v3
	v_max_f32_e32 v5, v5, v3
	v_max_f32_e32 v161, 0x1e3ce508, v161
	v_and_b32_e32 v185, 0xffff0000, v153
	v_max_f32_e32 v153, v159, v159
	v_max_f32_e32 v159, v170, v170
	v_rcp_f32_e32 v170, v161
	v_max_f32_e32 v161, v171, v171
	v_pk_mul_f32 v[4:5], v[4:5], v[150:151]
	v_max_f32_e32 v159, 0x1e3ce508, v159
	v_max_f32_e32 v161, 0x1e3ce508, v161
	v_pk_mul_f32 v[66:67], v[66:67], v[4:5]
	v_rcp_f32_e32 v159, v159
	v_rcp_f32_e32 v167, v161
	v_max_f32_e32 v4, 0x1e3ce508, v185
	v_rcp_f32_e32 v171, v4
	v_max_f32_e32 v161, v169, v169
	v_max_f32_e32 v152, v152, v3
	v_max_f32_e32 v153, v153, v3
	v_max_f32_e32 v160, v160, v3
	v_max_f32_e32 v161, v161, v3
	v_pk_mul_f32 v[150:151], v[160:161], v[166:167]
	v_max_f32_e32 v169, v172, v3
	v_pk_mul_f32 v[4:5], v[152:153], v[158:159]
	s_waitcnt vmcnt(4)
	v_lshlrev_b32_e32 v152, 16, v139
	v_and_b32_e32 v159, 0xffff0000, v139
	v_lshlrev_b32_e32 v139, 16, v140
	v_pk_mul_f32 v[68:69], v[68:69], v[150:151]
	v_pk_mul_f32 v[150:151], v[168:169], v[170:171]
	v_pk_mul_f32 v[64:65], v[64:65], v[150:151]
	v_pk_mul_f32 v[62:63], v[62:63], v[4:5]
	v_lshlrev_b32_e32 v4, 16, v146
	v_and_b32_e32 v5, 0xffff0000, v146
	v_lshlrev_b32_e32 v150, 16, v147
	v_and_b32_e32 v153, 0xffff0000, v147
	v_lshlrev_b32_e32 v146, 16, v148
	v_and_b32_e32 v147, 0xffff0000, v148
	v_lshlrev_b32_e32 v151, 16, v149
	v_and_b32_e32 v160, 0xffff0000, v149
	v_lshlrev_b32_e32 v148, 16, v138
	v_and_b32_e32 v149, 0xffff0000, v138
	v_max_f32_e32 v139, 0x1e3ce508, v139
	v_and_b32_e32 v158, 0xffff0000, v140
	v_max_f32_e32 v140, v146, v146
	v_rcp_f32_e32 v146, v139
	v_max_f32_e32 v139, v149, v149
	v_max_f32_e32 v138, 0x1e3ce508, v148
	v_max_f32_e32 v139, 0x1e3ce508, v139
	v_max_f32_e32 v149, v152, v152
	v_rcp_f32_e32 v138, v138
	v_rcp_f32_e32 v139, v139
	v_max_f32_e32 v149, 0x1e3ce508, v149
	v_lshlrev_b32_e32 v161, 16, v141
	v_max_f32_e32 v148, v150, v150
	v_rcp_f32_e32 v150, v149
	v_max_f32_e32 v149, v151, v151
	v_max_f32_e32 v4, v4, v4
	v_max_f32_e32 v5, v5, v5
	v_max_f32_e32 v152, v149, v3
	v_max_f32_e32 v149, v161, v161
	v_max_f32_e32 v4, v4, v3
	v_max_f32_e32 v5, v5, v3
	v_max_f32_e32 v149, 0x1e3ce508, v149
	v_and_b32_e32 v166, 0xffff0000, v141
	v_max_f32_e32 v141, v147, v147
	v_max_f32_e32 v147, v158, v158
	v_rcp_f32_e32 v158, v149
	v_max_f32_e32 v149, v159, v159
	v_pk_mul_f32 v[4:5], v[4:5], v[138:139]
	v_max_f32_e32 v149, 0x1e3ce508, v149
	v_pk_mul_f32 v[58:59], v[58:59], v[4:5]
	v_max_f32_e32 v4, v166, v166
	v_max_f32_e32 v147, 0x1e3ce508, v147
	v_rcp_f32_e32 v151, v149
	v_max_f32_e32 v4, 0x1e3ce508, v4
	v_rcp_f32_e32 v147, v147
	v_rcp_f32_e32 v159, v4
	v_max_f32_e32 v149, v153, v153
	v_max_f32_e32 v148, v148, v3
	v_max_f32_e32 v149, v149, v3
	v_max_f32_e32 v4, v160, v160
	v_max_f32_e32 v140, v140, v3
	v_max_f32_e32 v141, v141, v3
	v_pk_mul_f32 v[138:139], v[148:149], v[150:151]
	v_max_f32_e32 v153, v4, v3
	v_pk_mul_f32 v[60:61], v[60:61], v[138:139]
	v_pk_mul_f32 v[4:5], v[140:141], v[146:147]
	v_pk_mul_f32 v[138:139], v[152:153], v[158:159]
	v_pk_mul_f32 v[54:55], v[54:55], v[4:5]
	v_pk_mul_f32 v[56:57], v[56:57], v[138:139]
	v_lshl_add_u64 v[4:5], v[212:213], 0, s[66:67]
	v_lshl_add_u64 v[138:139], v[212:213], 0, s[28:29]
	global_load_dwordx4 v[158:161], v[4:5], off
	global_load_dwordx4 v[146:149], v[4:5], off offset:256
	global_load_dwordx4 v[150:153], v[138:139], off
	s_nop 0
	global_load_dwordx4 v[138:141], v[138:139], off offset:256
	s_waitcnt vmcnt(5)
	v_lshlrev_b32_e32 v168, 16, v155
	v_and_b32_e32 v171, 0xffff0000, v155
	v_lshlrev_b32_e32 v155, 16, v156
	v_lshlrev_b32_e32 v4, 16, v162
	v_and_b32_e32 v5, 0xffff0000, v162
	v_lshlrev_b32_e32 v166, 16, v163
	v_and_b32_e32 v169, 0xffff0000, v163
	v_lshlrev_b32_e32 v162, 16, v164
	v_and_b32_e32 v163, 0xffff0000, v164
	v_lshlrev_b32_e32 v167, 16, v165
	v_and_b32_e32 v172, 0xffff0000, v165
	v_lshlrev_b32_e32 v164, 16, v154
	v_and_b32_e32 v165, 0xffff0000, v154
	v_max_f32_e32 v155, 0x1e3ce508, v155
	v_and_b32_e32 v170, 0xffff0000, v156
	v_max_f32_e32 v156, v162, v162
	v_rcp_f32_e32 v162, v155
	v_max_f32_e32 v155, v165, v165
	v_max_f32_e32 v154, 0x1e3ce508, v164
	v_max_f32_e32 v155, 0x1e3ce508, v155
	v_max_f32_e32 v165, v168, v168
	v_rcp_f32_e32 v154, v154
	v_rcp_f32_e32 v155, v155
	v_max_f32_e32 v165, 0x1e3ce508, v165
	v_lshlrev_b32_e32 v173, 16, v157
	v_max_f32_e32 v164, v166, v166
	v_rcp_f32_e32 v166, v165
	v_max_f32_e32 v165, v167, v167
	v_max_f32_e32 v4, v4, v4
	v_max_f32_e32 v5, v5, v5
	v_max_f32_e32 v168, v165, v3
	v_max_f32_e32 v165, v173, v173
	v_max_f32_e32 v4, v4, v3
	v_max_f32_e32 v5, v5, v3
	v_max_f32_e32 v165, 0x1e3ce508, v165
	v_and_b32_e32 v185, 0xffff0000, v157
	v_max_f32_e32 v157, v163, v163
	v_max_f32_e32 v163, v170, v170
	v_rcp_f32_e32 v170, v165
	v_max_f32_e32 v165, v171, v171
	v_pk_mul_f32 v[4:5], v[4:5], v[154:155]
	v_max_f32_e32 v163, 0x1e3ce508, v163
	v_max_f32_e32 v165, 0x1e3ce508, v165
	v_pk_mul_f32 v[50:51], v[50:51], v[4:5]
	v_rcp_f32_e32 v163, v163
	v_rcp_f32_e32 v167, v165
	v_max_f32_e32 v4, 0x1e3ce508, v185
	v_rcp_f32_e32 v171, v4
	v_max_f32_e32 v165, v169, v169
	v_max_f32_e32 v156, v156, v3
	v_max_f32_e32 v157, v157, v3
	v_max_f32_e32 v164, v164, v3
	v_max_f32_e32 v165, v165, v3
	v_pk_mul_f32 v[154:155], v[164:165], v[166:167]
	v_max_f32_e32 v169, v172, v3
	v_pk_mul_f32 v[4:5], v[156:157], v[162:163]
	s_waitcnt vmcnt(4)
;     static __device__ __forceinline__ void unpack(const u32x4 g4, f32x4& g0, f32x4& g1) { g0 = (f32x4){bflo(g4.x), bfhi(g4.x), bflo(g4.y), bfhi(g4.y)}; g1 = (f32x4){bflo(g4.z), bfhi(g4.z), bflo(g4.w), bfhi(g4.w)}; }
;     __device__ __forceinline__ void mid(f32x4 (&acc)[2][2][4][2], const Unit& u, int wr, int wc, int fr, int fq, bool second) const {
;     ...
;         for (int gi = 0; gi < 8; ++gi) {
;             const int ai = gi >> 2, m = gi & 3;
;             if (gi < 7) { const size_t row2 = r0 + ((gi + 1) >> 2) * HALF + ((gi + 1) & 3) * 16;
; #pragma unroll
;                 for (int bj = 0; bj < 2; ++bj) { gn[(gi + 1) & 1][bj] = *(const u32x4*)(GT + row2 * ldg + on + col0 + bj * HALF); gd[(gi + 1) & 1][bj] = *(const u32x4*)(GT + row2 * ldg + od + col0 + bj * HALF); } }
;             asm volatile("" ::: "memory");
; #pragma unroll
;             for (int bj = 0; bj < 2; ++bj) {
;                 f32x4 n0, n1, d0, d1; unpack(gn[gi & 1][bj], n0, n1); unpack(gd[gi & 1][bj], d0, d1);
; #pragma unroll
;                 for (int j = 0; j < 4; ++j) {
;                     acc[ai][bj][m][0][j] *= fmaxf(n0[j], nfloor) * __builtin_amdgcn_rcpf(fmaxf(d0[j], 1e-20f));
;                     acc[ai][bj][m][1][j] *= fmaxf(n1[j], nfloor) * __builtin_amdgcn_rcpf(fmaxf(d1[j], 1e-20f)); }
;             }
	v_lshlrev_b32_e32 v156, 16, v135
	v_and_b32_e32 v163, 0xffff0000, v135
	v_lshlrev_b32_e32 v135, 16, v136
	v_pk_mul_f32 v[52:53], v[52:53], v[154:155]
	v_pk_mul_f32 v[154:155], v[168:169], v[170:171]
	v_pk_mul_f32 v[48:49], v[48:49], v[154:155]
	v_pk_mul_f32 v[46:47], v[46:47], v[4:5]
	v_lshlrev_b32_e32 v4, 16, v142
	v_and_b32_e32 v5, 0xffff0000, v142
	v_lshlrev_b32_e32 v154, 16, v143
	v_and_b32_e32 v157, 0xffff0000, v143
	v_lshlrev_b32_e32 v142, 16, v144
	v_and_b32_e32 v143, 0xffff0000, v144
	v_lshlrev_b32_e32 v155, 16, v145
	v_and_b32_e32 v164, 0xffff0000, v145
	v_lshlrev_b32_e32 v144, 16, v134
	v_and_b32_e32 v145, 0xffff0000, v134
	v_max_f32_e32 v135, 0x1e3ce508, v135
	v_and_b32_e32 v162, 0xffff0000, v136
	v_max_f32_e32 v136, v142, v142
	v_rcp_f32_e32 v142, v135
	v_max_f32_e32 v135, v145, v145
	v_max_f32_e32 v134, 0x1e3ce508, v144
	v_max_f32_e32 v135, 0x1e3ce508, v135
	v_max_f32_e32 v145, v156, v156
	v_rcp_f32_e32 v134, v134
	v_rcp_f32_e32 v135, v135
	v_max_f32_e32 v145, 0x1e3ce508, v145
	v_lshlrev_b32_e32 v165, 16, v137
	v_max_f32_e32 v144, v154, v154
	v_rcp_f32_e32 v154, v145
	v_max_f32_e32 v145, v155, v155
	v_max_f32_e32 v4, v4, v4
	v_max_f32_e32 v5, v5, v5
	v_max_f32_e32 v156, v145, v3
	v_max_f32_e32 v145, v165, v165
	v_max_f32_e32 v4, v4, v3
	v_max_f32_e32 v5, v5, v3
	v_max_f32_e32 v145, 0x1e3ce508, v145
	v_and_b32_e32 v166, 0xffff0000, v137
	v_max_f32_e32 v137, v143, v143
	v_max_f32_e32 v143, v162, v162
	v_rcp_f32_e32 v162, v145
	v_max_f32_e32 v145, v163, v163
	v_pk_mul_f32 v[4:5], v[4:5], v[134:135]
	v_max_f32_e32 v145, 0x1e3ce508, v145
	v_pk_mul_f32 v[42:43], v[42:43], v[4:5]
	v_max_f32_e32 v4, v166, v166
	v_max_f32_e32 v143, 0x1e3ce508, v143
	v_rcp_f32_e32 v155, v145
	v_max_f32_e32 v4, 0x1e3ce508, v4
	v_rcp_f32_e32 v143, v143
	v_rcp_f32_e32 v163, v4
	v_max_f32_e32 v145, v157, v157
	v_max_f32_e32 v144, v144, v3
	v_max_f32_e32 v145, v145, v3
	v_max_f32_e32 v4, v164, v164
	v_max_f32_e32 v136, v136, v3
	v_max_f32_e32 v137, v137, v3
	v_pk_mul_f32 v[134:135], v[144:145], v[154:155]
	v_max_f32_e32 v157, v4, v3
	v_pk_mul_f32 v[44:45], v[44:45], v[134:135]
	v_pk_mul_f32 v[4:5], v[136:137], v[142:143]
	v_pk_mul_f32 v[134:135], v[156:157], v[162:163]
	v_pk_mul_f32 v[38:39], v[38:39], v[4:5]
	v_pk_mul_f32 v[40:41], v[40:41], v[134:135]
	v_lshl_add_u64 v[4:5], v[214:215], 0, s[66:67]
	v_lshl_add_u64 v[134:135], v[214:215], 0, s[28:29]
	global_load_dwordx4 v[162:165], v[4:5], off
	global_load_dwordx4 v[142:145], v[4:5], off offset:256
	global_load_dwordx4 v[154:157], v[134:135], off
	s_nop 0
	global_load_dwordx4 v[134:137], v[134:135], off offset:256
	s_waitcnt vmcnt(5)
	v_lshlrev_b32_e32 v168, 16, v151
	v_and_b32_e32 v171, 0xffff0000, v151
	v_lshlrev_b32_e32 v151, 16, v152
	v_lshlrev_b32_e32 v4, 16, v158
	v_and_b32_e32 v5, 0xffff0000, v158
	v_lshlrev_b32_e32 v166, 16, v159
	v_and_b32_e32 v169, 0xffff0000, v159
	v_lshlrev_b32_e32 v158, 16, v160
	v_and_b32_e32 v159, 0xffff0000, v160
	v_lshlrev_b32_e32 v167, 16, v161
	v_and_b32_e32 v172, 0xffff0000, v161
	v_lshlrev_b32_e32 v160, 16, v150
	v_and_b32_e32 v161, 0xffff0000, v150
	v_max_f32_e32 v151, 0x1e3ce508, v151
	v_and_b32_e32 v170, 0xffff0000, v152
	v_max_f32_e32 v152, v158, v158
	v_rcp_f32_e32 v158, v151
	v_max_f32_e32 v151, v161, v161
	v_max_f32_e32 v150, 0x1e3ce508, v160
	v_max_f32_e32 v151, 0x1e3ce508, v151
	v_max_f32_e32 v161, v168, v168
	v_rcp_f32_e32 v150, v150
	v_rcp_f32_e32 v151, v151
	v_max_f32_e32 v161, 0x1e3ce508, v161
	v_lshlrev_b32_e32 v173, 16, v153
	v_max_f32_e32 v160, v166, v166
	v_rcp_f32_e32 v166, v161
	v_max_f32_e32 v161, v167, v167
	v_max_f32_e32 v4, v4, v4
	v_max_f32_e32 v5, v5, v5
	v_max_f32_e32 v168, v161, v3
	v_max_f32_e32 v161, v173, v173
	v_max_f32_e32 v4, v4, v3
	v_max_f32_e32 v5, v5, v3
	v_max_f32_e32 v161, 0x1e3ce508, v161
	v_and_b32_e32 v185, 0xffff0000, v153
	v_max_f32_e32 v153, v159, v159
	v_max_f32_e32 v159, v170, v170
	v_rcp_f32_e32 v170, v161
	v_max_f32_e32 v161, v171, v171
	v_pk_mul_f32 v[4:5], v[4:5], v[150:151]
	v_max_f32_e32 v159, 0x1e3ce508, v159
	v_max_f32_e32 v161, 0x1e3ce508, v161
	v_pk_mul_f32 v[34:35], v[34:35], v[4:5]
	v_rcp_f32_e32 v159, v159
	v_rcp_f32_e32 v167, v161
	v_max_f32_e32 v4, 0x1e3ce508, v185
	v_rcp_f32_e32 v171, v4
	v_max_f32_e32 v161, v169, v169
	v_max_f32_e32 v152, v152, v3
	v_max_f32_e32 v153, v153, v3
	v_max_f32_e32 v160, v160, v3
	v_max_f32_e32 v161, v161, v3
	v_pk_mul_f32 v[150:151], v[160:161], v[166:167]
	v_max_f32_e32 v169, v172, v3
	v_pk_mul_f32 v[4:5], v[152:153], v[158:159]
	s_waitcnt vmcnt(4)
;     static __device__ __forceinline__ void unpack(const u32x4 g4, f32x4& g0, f32x4& g1) { g0 = (f32x4){bflo(g4.x), bfhi(g4.x), bflo(g4.y), bfhi(g4.y)}; g1 = (f32x4){bflo(g4.z), bfhi(g4.z), bflo(g4.w), bfhi(g4.w)}; }
;     __device__ __forceinline__ void mid(f32x4 (&acc)[2][2][4][2], const Unit& u, int wr, int wc, int fr, int fq, bool second) const {
;     ...
;         for (int gi = 0; gi < 8; ++gi) {
;             const int ai = gi >> 2, m = gi & 3;
;             if (gi < 7) { const size_t row2 = r0 + ((gi + 1) >> 2) * HALF + ((gi + 1) & 3) * 16;
; #pragma unroll
;                 for (int bj = 0; bj < 2; ++bj) { gn[(gi + 1) & 1][bj] = *(const u32x4*)(GT + row2 * ldg + on + col0 + bj * HALF); gd[(gi + 1) & 1][bj] = *(const u32x4*)(GT + row2 * ldg + od + col0 + bj * HALF); } }
;             asm volatile("" ::: "memory");
; #pragma unroll
;             for (int bj = 0; bj < 2; ++bj) {
;                 f32x4 n0, n1, d0, d1; unpack(gn[gi & 1][bj], n0, n1); unpack(gd[gi & 1][bj], d0, d1);
; #pragma unroll
;                 for (int j = 0; j < 4; ++j) {
;                     acc[ai][bj][m][0][j] *= fmaxf(n0[j], nfloor) * __builtin_amdgcn_rcpf(fmaxf(d0[j], 1e-20f));
;                     acc[ai][bj][m][1][j] *= fmaxf(n1[j], nfloor) * __builtin_amdgcn_rcpf(fmaxf(d1[j], 1e-20f)); }
;             }
	v_lshlrev_b32_e32 v152, 16, v139
	v_and_b32_e32 v159, 0xffff0000, v139
	v_lshlrev_b32_e32 v139, 16, v140
	v_pk_mul_f32 v[36:37], v[36:37], v[150:151]
	v_pk_mul_f32 v[150:151], v[168:169], v[170:171]
	v_pk_mul_f32 v[32:33], v[32:33], v[150:151]
	v_pk_mul_f32 v[30:31], v[30:31], v[4:5]
	v_lshlrev_b32_e32 v4, 16, v146
	v_and_b32_e32 v5, 0xffff0000, v146
	v_lshlrev_b32_e32 v150, 16, v147
	v_and_b32_e32 v153, 0xffff0000, v147
	v_lshlrev_b32_e32 v146, 16, v148
	v_and_b32_e32 v147, 0xffff0000, v148
	v_lshlrev_b32_e32 v151, 16, v149
	v_and_b32_e32 v160, 0xffff0000, v149
	v_lshlrev_b32_e32 v148, 16, v138
	v_and_b32_e32 v149, 0xffff0000, v138
	v_max_f32_e32 v139, 0x1e3ce508, v139
	v_and_b32_e32 v158, 0xffff0000, v140
	v_max_f32_e32 v140, v146, v146
	v_rcp_f32_e32 v146, v139
	v_max_f32_e32 v139, v149, v149
	v_max_f32_e32 v138, 0x1e3ce508, v148
	v_max_f32_e32 v139, 0x1e3ce508, v139
	v_max_f32_e32 v149, v152, v152
	v_rcp_f32_e32 v138, v138
	v_rcp_f32_e32 v139, v139
	v_max_f32_e32 v149, 0x1e3ce508, v149
	v_lshlrev_b32_e32 v161, 16, v141
	v_max_f32_e32 v148, v150, v150
	v_rcp_f32_e32 v150, v149
	v_max_f32_e32 v149, v151, v151
	v_max_f32_e32 v4, v4, v4
	v_max_f32_e32 v5, v5, v5
	v_max_f32_e32 v152, v149, v3
	v_max_f32_e32 v149, v161, v161
	v_max_f32_e32 v4, v4, v3
	v_max_f32_e32 v5, v5, v3
	v_max_f32_e32 v149, 0x1e3ce508, v149
	v_and_b32_e32 v166, 0xffff0000, v141
	v_max_f32_e32 v141, v147, v147
	v_max_f32_e32 v147, v158, v158
	v_rcp_f32_e32 v158, v149
	v_max_f32_e32 v149, v159, v159
	v_pk_mul_f32 v[4:5], v[4:5], v[138:139]
	v_max_f32_e32 v149, 0x1e3ce508, v149
	v_pk_mul_f32 v[26:27], v[26:27], v[4:5]
	v_max_f32_e32 v4, v166, v166
	v_rcp_f32_e32 v151, v149
	v_max_f32_e32 v4, 0x1e3ce508, v4
	v_rcp_f32_e32 v159, v4
	v_max_f32_e32 v147, 0x1e3ce508, v147
	v_max_f32_e32 v149, v153, v153
	v_rcp_f32_e32 v147, v147
	v_max_f32_e32 v148, v148, v3
	v_max_f32_e32 v149, v149, v3
	v_max_f32_e32 v4, v160, v160
	v_pk_mul_f32 v[138:139], v[148:149], v[150:151]
	v_max_f32_e32 v153, v4, v3
	v_pk_mul_f32 v[28:29], v[28:29], v[138:139]
	v_pk_mul_f32 v[138:139], v[152:153], v[158:159]
	v_max_f32_e32 v140, v140, v3
	v_max_f32_e32 v141, v141, v3
	v_pk_mul_f32 v[24:25], v[24:25], v[138:139]
	s_waitcnt vmcnt(3)
	v_lshlrev_b32_e32 v139, 16, v164
	v_pk_mul_f32 v[4:5], v[140:141], v[146:147]
	s_waitcnt vmcnt(1)
	v_lshlrev_b32_e32 v146, 16, v156
	v_max_f32_e32 v140, v139, v3
	v_lshlrev_b32_e32 v138, 16, v154
	v_and_b32_e32 v147, 0xffff0000, v154
	v_max_f32_e32 v139, 0x1e3ce508, v146
	v_rcp_f32_e32 v146, v139
	v_max_f32_e32 v139, v147, v147
	v_max_f32_e32 v138, 0x1e3ce508, v138
	v_max_f32_e32 v139, 0x1e3ce508, v139
	v_lshlrev_b32_e32 v151, 16, v165
	v_rcp_f32_e32 v138, v138
	v_rcp_f32_e32 v139, v139
	v_pk_mul_f32 v[22:23], v[22:23], v[4:5]
	v_lshlrev_b32_e32 v4, 16, v162
	v_and_b32_e32 v5, 0xffff0000, v162
	v_and_b32_e32 v152, 0xffff0000, v156
	v_lshlrev_b32_e32 v154, 16, v157
	v_max_f32_e32 v147, v152, v152
	v_max_f32_e32 v152, v151, v3
	v_lshlrev_b32_e32 v150, 16, v155
	v_and_b32_e32 v155, 0xffff0000, v155
	v_max_f32_e32 v4, v4, v3
	v_max_f32_e32 v5, v5, v3
	v_max_f32_e32 v151, 0x1e3ce508, v154
	v_and_b32_e32 v156, 0xffff0000, v157
	v_rcp_f32_e32 v154, v151
	v_max_f32_e32 v151, v155, v155
	v_pk_mul_f32 v[4:5], v[4:5], v[138:139]
	v_max_f32_e32 v147, 0x1e3ce508, v147
	v_max_f32_e32 v150, 0x1e3ce508, v150
	v_max_f32_e32 v151, 0x1e3ce508, v151
	v_pk_mul_f32 v[18:19], v[18:19], v[4:5]
	v_rcp_f32_e32 v147, v147
	v_rcp_f32_e32 v150, v150
	v_rcp_f32_e32 v151, v151
	v_max_f32_e32 v4, 0x1e3ce508, v156
	v_lshlrev_b32_e32 v148, 16, v163
	v_and_b32_e32 v149, 0xffff0000, v163
	v_and_b32_e32 v141, 0xffff0000, v164
	v_rcp_f32_e32 v155, v4
	v_and_b32_e32 v153, 0xffff0000, v165
	v_max_f32_e32 v141, v141, v141
	v_max_f32_e32 v148, v148, v148
	v_max_f32_e32 v149, v149, v149
	v_max_f32_e32 v141, v141, v3
	v_max_f32_e32 v148, v148, v3
	v_max_f32_e32 v149, v149, v3
	v_pk_mul_f32 v[138:139], v[148:149], v[150:151]
	v_max_f32_e32 v153, v153, v3
	v_pk_mul_f32 v[4:5], v[140:141], v[146:147]
	s_waitcnt vmcnt(0)
	v_lshlrev_b32_e32 v146, 16, v135
	v_and_b32_e32 v147, 0xffff0000, v135
	v_lshlrev_b32_e32 v135, 16, v136
	v_pk_mul_f32 v[20:21], v[20:21], v[138:139]
	v_pk_mul_f32 v[138:139], v[152:153], v[154:155]
	v_pk_mul_f32 v[16:17], v[16:17], v[138:139]
	v_pk_mul_f32 v[14:15], v[14:15], v[4:5]
	v_lshlrev_b32_e32 v4, 16, v142
	v_and_b32_e32 v5, 0xffff0000, v142
	v_lshlrev_b32_e32 v138, 16, v144
	v_and_b32_e32 v139, 0xffff0000, v144
	v_lshlrev_b32_e32 v142, 16, v134
	v_and_b32_e32 v144, 0xffff0000, v134
	v_max_f32_e32 v135, 0x1e3ce508, v135
	v_and_b32_e32 v148, 0xffff0000, v136
	v_max_f32_e32 v136, v138, v138
	v_rcp_f32_e32 v138, v135
	v_max_f32_e32 v135, v144, v144
	v_max_f32_e32 v134, 0x1e3ce508, v142
	v_max_f32_e32 v135, 0x1e3ce508, v135
	v_lshlrev_b32_e32 v140, 16, v143
	v_and_b32_e32 v141, 0xffff0000, v143
	v_lshlrev_b32_e32 v143, 16, v145
	v_rcp_f32_e32 v134, v134
	v_rcp_f32_e32 v135, v135
	v_lshlrev_b32_e32 v149, 16, v137
	v_max_f32_e32 v143, v143, v143
	v_max_f32_e32 v4, v4, v4
	v_max_f32_e32 v5, v5, v5
	v_max_f32_e32 v144, v143, v3
	v_max_f32_e32 v4, v4, v3
	v_max_f32_e32 v5, v5, v3
	v_max_f32_e32 v143, 0x1e3ce508, v149
	v_and_b32_e32 v150, 0xffff0000, v137
	v_max_f32_e32 v142, v146, v146
	v_rcp_f32_e32 v146, v143
	v_max_f32_e32 v143, v147, v147
	v_pk_mul_f32 v[4:5], v[4:5], v[134:135]
	v_max_f32_e32 v137, v139, v139
	v_max_f32_e32 v139, v148, v148
	v_max_f32_e32 v142, 0x1e3ce508, v142
	v_max_f32_e32 v143, 0x1e3ce508, v143
	v_pk_mul_f32 v[10:11], v[10:11], v[4:5]
	v_max_f32_e32 v139, 0x1e3ce508, v139
	v_rcp_f32_e32 v142, v142
	v_rcp_f32_e32 v143, v143
	v_max_f32_e32 v4, 0x1e3ce508, v150
	v_rcp_f32_e32 v139, v139
	v_rcp_f32_e32 v147, v4
	v_and_b32_e32 v145, 0xffff0000, v145
	v_max_f32_e32 v140, v140, v140
	v_max_f32_e32 v141, v141, v141
	v_max_f32_e32 v140, v140, v3
	v_max_f32_e32 v141, v141, v3
	v_max_f32_e32 v136, v136, v3
	v_max_f32_e32 v137, v137, v3
	v_pk_mul_f32 v[134:135], v[140:141], v[142:143]
	v_max_f32_e32 v145, v145, v3
	v_pk_mul_f32 v[12:13], v[12:13], v[134:135]
	v_pk_mul_f32 v[4:5], v[136:137], v[138:139]
	v_pk_mul_f32 v[134:135], v[144:145], v[146:147]
	v_pk_mul_f32 v[6:7], v[6:7], v[4:5]
	v_pk_mul_f32 v[8:9], v[8:9], v[134:135]

; __device__ __forceinline__ unsigned cvt_pk_bf16(float lo, float hi) { const f2_t_ v = {lo, hi}; return __builtin_bit_cast(unsigned, __builtin_convertvector(v, bf2_t_)); }
;     static __device__ __forceinline__ void unpack(const u32x4 g4, f32x4& g0, f32x4& g1) { g0 = (f32x4){bflo(g4.x), bfhi(g4.x), bflo(g4.y), bfhi(g4.y)}; g1 = (f32x4){bflo(g4.z), bfhi(g4.z), bflo(g4.w), bfhi(g4.w)}; }
;     __device__ __forceinline__ void operator()(const f32x4 (&acc)[2][2][4][2], const Unit& u, int wr, int wc, int fr, int fq) const {
;     ...
;         u32x4 gw[2][2];
; #pragma unroll
;         for (int bj = 0; bj < 2; ++bj) gw[0][bj] = *(const u32x4*)(GT + r0 * ldg + 4096 + col0 + bj * HALF);
; #pragma unroll
;         for (int gi = 0; gi < 8; ++gi) {
;             const int ai = gi >> 2, m = gi & 3; const size_t row = r0 + ai * HALF + m * 16;
;             if (gi < 7) { const size_t row2 = r0 + ((gi + 1) >> 2) * HALF + ((gi + 1) & 3) * 16;
; #pragma unroll
;                 for (int bj = 0; bj < 2; ++bj) gw[(gi + 1) & 1][bj] = *(const u32x4*)(GT + row2 * ldg + 4096 + col0 + bj * HALF); }
;             asm volatile("" ::: "memory");
; #pragma unroll
;             for (int bj = 0; bj < 2; ++bj) {
;                 f32x4 g0, g1; unpack(gw[gi & 1][bj], g0, g1);
;                 f32x4 v0, v1;
; #pragma unroll
;                 for (int j = 0; j < 4; ++j) { v0[j] = acc[ai][bj][m][0][j] * fmaxf(g0[j], 1e-20f); v1[j] = acc[ai][bj][m][1][j] * fmaxf(g1[j], 1e-20f); }
;                 u32x4 w; w.x = cvt_pk_bf16(v0[0], v0[1]); w.y = cvt_pk_bf16(v0[2], v0[3]); w.z = cvt_pk_bf16(v1[0], v1[1]); w.w = cvt_pk_bf16(v1[2], v1[3]);
;                 *(u32x4*)(O + row * 2048 + col0 + bj * HALF) = w;
;             }
.LBB0_998:
	v_mov_b64_e32 v[146:147], s[16:17]
	v_ashrrev_i32_e32 v187, 31, v186
	v_mad_i64_i32 v[134:135], s[26:27], v184, s83, v[146:147]
	v_lshlrev_b64 v[4:5], 1, v[186:187]
	v_lshl_add_u64 v[150:151], v[134:135], 0, v[4:5]
	v_add_co_u32_e32 v136, vcc, 0x2000, v150
	s_mov_b64 s[28:29], 0x2000
	s_nop 0
	v_addc_co_u32_e32 v137, vcc, 0, v151, vcc
	v_lshl_add_u64 v[134:135], v[150:151], 0, s[28:29]
	global_load_dwordx4 v[152:155], v[136:137], off
	global_load_dwordx4 v[142:145], v[134:135], off offset:256
	s_mov_b64 s[30:31], 0x32000
	v_add_co_u32_e32 v136, vcc, 0x32000, v150
	v_lshl_add_u64 v[134:135], v[150:151], 0, s[30:31]
	s_nop 0
	v_addc_co_u32_e32 v137, vcc, 0, v151, vcc
	global_load_dwordx4 v[138:141], v[136:137], off
	s_nop 0
	global_load_dwordx4 v[134:137], v[134:135], off offset:256
	v_ashrrev_i32_e32 v185, 31, v184
	v_lshlrev_b64 v[148:149], 12, v[184:185]
	s_mov_b64 s[60:61], 0x62000
	s_mov_b64 s[26:27], 0x92000
	s_waitcnt vmcnt(3)
	v_lshlrev_b32_e32 v3, 16, v152
	v_lshlrev_b32_e32 v157, 16, v153
	v_and_b32_e32 v158, 0xffff0000, v153
	v_lshlrev_b32_e32 v153, 16, v154
	v_and_b32_e32 v156, 0xffff0000, v152
	v_max_f32_e32 v152, 0x1e3ce508, v3
	v_and_b32_e32 v159, 0xffff0000, v154
	v_max_f32_e32 v154, 0x1e3ce508, v153
	v_max_f32_e32 v153, 0x1e3ce508, v156
	v_lshlrev_b32_e32 v160, 16, v155
	v_and_b32_e32 v161, 0xffff0000, v155
	v_max_f32_e32 v155, 0x1e3ce508, v159
	v_pk_mul_f32 v[126:127], v[126:127], v[152:153]
	v_max_f32_e32 v152, 0x1e3ce508, v157
	v_pk_mul_f32 v[130:131], v[130:131], v[154:155]
	v_max_f32_e32 v154, 0x1e3ce508, v160
	v_max_f32_e32 v153, 0x1e3ce508, v158
	v_max_f32_e32 v155, 0x1e3ce508, v161
	v_pk_mul_f32 v[152:153], v[128:129], v[152:153]
	v_pk_mul_f32 v[132:133], v[132:133], v[154:155]
	v_cvt_pk_bf16_f32 v128, v126, v127
	v_lshl_add_u64 v[126:127], s[18:19], 0, v[148:149]
	v_cvt_pk_bf16_f32 v129, v152, v153
	v_cvt_pk_bf16_f32 v130, v130, v131
	v_cvt_pk_bf16_f32 v131, v132, v133
	v_lshl_add_u64 v[126:127], v[126:127], 0, v[4:5]
	s_waitcnt vmcnt(2)
	v_lshlrev_b32_e32 v3, 16, v142
	global_store_dwordx4 v[126:127], v[128:131], off
	v_max_f32_e32 v3, v3, v3
	v_lshlrev_b32_e32 v132, 16, v143
	v_lshlrev_b32_e32 v130, 16, v144
	v_and_b32_e32 v129, 0xffff0000, v142
	v_max_f32_e32 v128, 0x1e3ce508, v3
	v_and_b32_e32 v131, 0xffff0000, v144
	v_max_f32_e32 v130, 0x1e3ce508, v130
	v_max_f32_e32 v129, 0x1e3ce508, v129
	v_lshlrev_b32_e32 v142, 16, v145
	v_max_f32_e32 v131, 0x1e3ce508, v131
	v_and_b32_e32 v133, 0xffff0000, v143
	v_pk_mul_f32 v[122:123], v[122:123], v[128:129]
	v_pk_mul_f32 v[128:129], v[118:119], v[130:131]
	v_max_f32_e32 v118, 0x1e3ce508, v132
	v_and_b32_e32 v143, 0xffff0000, v145
	v_max_f32_e32 v130, 0x1e3ce508, v142
	v_max_f32_e32 v119, 0x1e3ce508, v133
	v_max_f32_e32 v131, 0x1e3ce508, v143
	v_pk_mul_f32 v[124:125], v[124:125], v[118:119]
	v_pk_mul_f32 v[130:131], v[120:121], v[130:131]
	v_cvt_pk_bf16_f32 v118, v122, v123
	v_cvt_pk_bf16_f32 v119, v124, v125
	v_cvt_pk_bf16_f32 v120, v128, v129
	v_cvt_pk_bf16_f32 v121, v130, v131
	s_waitcnt vmcnt(2)
	v_lshlrev_b32_e32 v3, 16, v138
	global_store_dwordx4 v[126:127], v[118:121], off offset:256
	v_lshlrev_b32_e32 v130, 16, v140
	v_max_f32_e32 v3, v3, v3
	v_add_co_u32_e32 v118, vcc, s73, v150
	v_lshl_add_u64 v[122:123], v[150:151], 0, s[60:61]
	s_nop 0
	v_addc_co_u32_e32 v119, vcc, 0, v151, vcc
	v_and_b32_e32 v129, 0xffff0000, v138
	v_max_f32_e32 v128, 0x1e3ce508, v3
	v_max_f32_e32 v3, v130, v130
	global_load_dwordx4 v[118:121], v[118:119], off
	s_nop 0
	global_load_dwordx4 v[122:125], v[122:123], off offset:256
	v_and_b32_e32 v131, 0xffff0000, v140
	v_max_f32_e32 v130, 0x1e3ce508, v3
	v_lshlrev_b32_e32 v132, 16, v139
	v_max_f32_e32 v129, 0x1e3ce508, v129
	v_lshlrev_b32_e32 v138, 16, v141
	v_max_f32_e32 v131, 0x1e3ce508, v131
	v_and_b32_e32 v133, 0xffff0000, v139
	v_pk_mul_f32 v[114:115], v[114:115], v[128:129]
	v_pk_mul_f32 v[128:129], v[110:111], v[130:131]
	v_max_f32_e32 v110, 0x1e3ce508, v132
	v_and_b32_e32 v139, 0xffff0000, v141
	v_max_f32_e32 v130, 0x1e3ce508, v138
	v_max_f32_e32 v111, 0x1e3ce508, v133
	v_or_b32_e32 v126, 0x10000, v148
	v_mov_b32_e32 v127, v149
	v_max_f32_e32 v131, 0x1e3ce508, v139
	v_pk_mul_f32 v[116:117], v[116:117], v[110:111]
	v_pk_mul_f32 v[130:131], v[112:113], v[130:131]
	v_cvt_pk_bf16_f32 v110, v114, v115
	v_lshl_add_u64 v[114:115], s[18:19], 0, v[126:127]
	v_cvt_pk_bf16_f32 v111, v116, v117
	v_cvt_pk_bf16_f32 v112, v128, v129
	v_cvt_pk_bf16_f32 v113, v130, v131
	v_lshl_add_u64 v[114:115], v[114:115], 0, v[4:5]
	s_waitcnt vmcnt(4)
	v_lshlrev_b32_e32 v3, 16, v134
	global_store_dwordx4 v[114:115], v[110:113], off
	v_max_f32_e32 v3, v3, v3
	v_lshlrev_b32_e32 v116, 16, v135
	v_lshlrev_b32_e32 v112, 16, v136
	v_and_b32_e32 v111, 0xffff0000, v134
	v_max_f32_e32 v110, 0x1e3ce508, v3
	v_and_b32_e32 v113, 0xffff0000, v136
	v_max_f32_e32 v112, 0x1e3ce508, v112
	v_max_f32_e32 v111, 0x1e3ce508, v111
	v_lshlrev_b32_e32 v126, 16, v137
	v_max_f32_e32 v113, 0x1e3ce508, v113
	v_and_b32_e32 v117, 0xffff0000, v135
	v_pk_mul_f32 v[106:107], v[106:107], v[110:111]
	v_pk_mul_f32 v[110:111], v[102:103], v[112:113]
	v_max_f32_e32 v102, 0x1e3ce508, v116
	v_and_b32_e32 v127, 0xffff0000, v137
	v_max_f32_e32 v112, 0x1e3ce508, v126
	v_max_f32_e32 v103, 0x1e3ce508, v117
	v_max_f32_e32 v113, 0x1e3ce508, v127
	v_pk_mul_f32 v[108:109], v[108:109], v[102:103]
	v_pk_mul_f32 v[112:113], v[104:105], v[112:113]
	v_cvt_pk_bf16_f32 v102, v106, v107
	v_cvt_pk_bf16_f32 v103, v108, v109
	v_cvt_pk_bf16_f32 v104, v110, v111
	v_cvt_pk_bf16_f32 v105, v112, v113
	v_lshl_add_u64 v[106:107], v[150:151], 0, s[26:27]
	s_mov_b32 s26, 0x92000
	global_store_dwordx4 v[114:115], v[102:105], off offset:256
	v_or_b32_e32 v110, 0x20000, v148
	v_mov_b32_e32 v111, v149
	v_add_co_u32_e32 v102, vcc, s26, v150
	s_mov_b64 s[26:27], 0x182000
	s_nop 0
	v_addc_co_u32_e32 v103, vcc, 0, v151, vcc
	global_load_dwordx4 v[102:105], v[102:103], off
	s_nop 0
	global_load_dwordx4 v[106:109], v[106:107], off offset:256
	s_waitcnt vmcnt(5)
; __device__ __forceinline__ unsigned cvt_pk_bf16(float lo, float hi) { const f2_t_ v = {lo, hi}; return __builtin_bit_cast(unsigned, __builtin_convertvector(v, bf2_t_)); }
;     static __device__ __forceinline__ void unpack(const u32x4 g4, f32x4& g0, f32x4& g1) { g0 = (f32x4){bflo(g4.x), bfhi(g4.x), bflo(g4.y), bfhi(g4.y)}; g1 = (f32x4){bflo(g4.z), bfhi(g4.z), bflo(g4.w), bfhi(g4.w)}; }
;     __device__ __forceinline__ void operator()(const f32x4 (&acc)[2][2][4][2], const Unit& u, int wr, int wc, int fr, int fq) const {
;     ...
;             if (gi < 7) { const size_t row2 = r0 + ((gi + 1) >> 2) * HALF + ((gi + 1) & 3) * 16;
; #pragma unroll
;                 for (int bj = 0; bj < 2; ++bj) gw[(gi + 1) & 1][bj] = *(const u32x4*)(GT + row2 * ldg + 4096 + col0 + bj * HALF); }
;             asm volatile("" ::: "memory");
; #pragma unroll
;             for (int bj = 0; bj < 2; ++bj) {
;                 f32x4 g0, g1; unpack(gw[gi & 1][bj], g0, g1);
;                 f32x4 v0, v1;
; #pragma unroll
;                 for (int j = 0; j < 4; ++j) { v0[j] = acc[ai][bj][m][0][j] * fmaxf(g0[j], 1e-20f); v1[j] = acc[ai][bj][m][1][j] * fmaxf(g1[j], 1e-20f); }
;                 u32x4 w; w.x = cvt_pk_bf16(v0[0], v0[1]); w.y = cvt_pk_bf16(v0[2], v0[3]); w.z = cvt_pk_bf16(v1[0], v1[1]); w.w = cvt_pk_bf16(v1[2], v1[3]);
;                 *(u32x4*)(O + row * 2048 + col0 + bj * HALF) = w;
;             }
	v_lshlrev_b32_e32 v3, 16, v118
	v_lshlrev_b32_e32 v114, 16, v120
	v_and_b32_e32 v113, 0xffff0000, v118
	v_max_f32_e32 v112, 0x1e3ce508, v3
	v_and_b32_e32 v115, 0xffff0000, v120
	v_max_f32_e32 v114, 0x1e3ce508, v114
	v_lshlrev_b32_e32 v116, 16, v119
	v_max_f32_e32 v113, 0x1e3ce508, v113
	v_lshlrev_b32_e32 v118, 16, v121
	v_max_f32_e32 v115, 0x1e3ce508, v115
	v_and_b32_e32 v117, 0xffff0000, v119
	v_pk_mul_f32 v[98:99], v[98:99], v[112:113]
	v_pk_mul_f32 v[112:113], v[94:95], v[114:115]
	v_max_f32_e32 v94, 0x1e3ce508, v116
	v_and_b32_e32 v119, 0xffff0000, v121
	v_max_f32_e32 v114, 0x1e3ce508, v118
	v_max_f32_e32 v95, 0x1e3ce508, v117
	v_max_f32_e32 v115, 0x1e3ce508, v119
	v_pk_mul_f32 v[100:101], v[100:101], v[94:95]
	v_pk_mul_f32 v[114:115], v[96:97], v[114:115]
	v_cvt_pk_bf16_f32 v94, v98, v99
	v_lshl_add_u64 v[98:99], s[18:19], 0, v[110:111]
	v_cvt_pk_bf16_f32 v95, v100, v101
	v_cvt_pk_bf16_f32 v96, v112, v113
	v_cvt_pk_bf16_f32 v97, v114, v115
	v_lshl_add_u64 v[98:99], v[98:99], 0, v[4:5]
	s_waitcnt vmcnt(4)
	v_lshlrev_b32_e32 v3, 16, v122
	global_store_dwordx4 v[98:99], v[94:97], off
	v_max_f32_e32 v3, v3, v3
	v_lshlrev_b32_e32 v100, 16, v123
	v_lshlrev_b32_e32 v96, 16, v124
	v_and_b32_e32 v95, 0xffff0000, v122
	v_max_f32_e32 v94, 0x1e3ce508, v3
	v_and_b32_e32 v97, 0xffff0000, v124
	v_max_f32_e32 v96, 0x1e3ce508, v96
	v_max_f32_e32 v95, 0x1e3ce508, v95
	v_lshlrev_b32_e32 v110, 16, v125
	v_max_f32_e32 v97, 0x1e3ce508, v97
	v_and_b32_e32 v101, 0xffff0000, v123
	v_pk_mul_f32 v[90:91], v[90:91], v[94:95]
	v_pk_mul_f32 v[94:95], v[86:87], v[96:97]
	v_max_f32_e32 v86, 0x1e3ce508, v100
	v_and_b32_e32 v111, 0xffff0000, v125
	v_max_f32_e32 v96, 0x1e3ce508, v110
	v_max_f32_e32 v87, 0x1e3ce508, v101
	v_max_f32_e32 v97, 0x1e3ce508, v111
	v_pk_mul_f32 v[92:93], v[92:93], v[86:87]
	v_pk_mul_f32 v[96:97], v[88:89], v[96:97]
	v_cvt_pk_bf16_f32 v86, v90, v91
	v_cvt_pk_bf16_f32 v87, v92, v93
	v_cvt_pk_bf16_f32 v88, v94, v95
	v_cvt_pk_bf16_f32 v89, v96, v97
	global_store_dwordx4 v[98:99], v[86:89], off offset:256
	v_lshl_add_u64 v[90:91], v[150:151], 0, s[26:27]
	s_mov_b32 s26, 0x182000
	v_add_co_u32_e32 v86, vcc, s26, v150
	v_or_b32_e32 v94, 0x30000, v148
	s_nop 0
	v_addc_co_u32_e32 v87, vcc, 0, v151, vcc
	s_waitcnt vmcnt(3)
	v_lshlrev_b32_e32 v3, 16, v102
	v_lshlrev_b32_e32 v98, 16, v104
	v_max_f32_e32 v3, v3, v3
	v_and_b32_e32 v97, 0xffff0000, v102
	v_max_f32_e32 v96, 0x1e3ce508, v3
	v_and_b32_e32 v99, 0xffff0000, v104
	v_max_f32_e32 v98, 0x1e3ce508, v98
	v_lshlrev_b32_e32 v100, 16, v103
	v_max_f32_e32 v97, 0x1e3ce508, v97
	v_lshlrev_b32_e32 v102, 16, v105
	v_max_f32_e32 v99, 0x1e3ce508, v99
	global_load_dwordx4 v[86:89], v[86:87], off
	s_nop 0
	global_load_dwordx4 v[90:93], v[90:91], off offset:256
	v_and_b32_e32 v101, 0xffff0000, v103
	v_pk_mul_f32 v[82:83], v[82:83], v[96:97]
	v_pk_mul_f32 v[96:97], v[78:79], v[98:99]
	v_max_f32_e32 v78, 0x1e3ce508, v100
	v_and_b32_e32 v103, 0xffff0000, v105
	v_max_f32_e32 v98, 0x1e3ce508, v102
	v_max_f32_e32 v79, 0x1e3ce508, v101
	v_mov_b32_e32 v95, v149
	v_max_f32_e32 v99, 0x1e3ce508, v103
	v_pk_mul_f32 v[84:85], v[84:85], v[78:79]
	v_pk_mul_f32 v[98:99], v[80:81], v[98:99]
	v_cvt_pk_bf16_f32 v78, v82, v83
	v_lshl_add_u64 v[82:83], s[18:19], 0, v[94:95]
	v_cvt_pk_bf16_f32 v79, v84, v85
	v_cvt_pk_bf16_f32 v80, v96, v97
	v_cvt_pk_bf16_f32 v81, v98, v99
	v_lshl_add_u64 v[82:83], v[82:83], 0, v[4:5]
	s_waitcnt vmcnt(4)
	v_lshlrev_b32_e32 v3, 16, v106
	global_store_dwordx4 v[82:83], v[78:81], off
	v_max_f32_e32 v3, v3, v3
	v_lshlrev_b32_e32 v84, 16, v107
	v_lshlrev_b32_e32 v80, 16, v108
	v_and_b32_e32 v79, 0xffff0000, v106
	v_max_f32_e32 v78, 0x1e3ce508, v3
	v_and_b32_e32 v81, 0xffff0000, v108
	v_max_f32_e32 v80, 0x1e3ce508, v80
	v_max_f32_e32 v79, 0x1e3ce508, v79
	v_lshlrev_b32_e32 v94, 16, v109
	v_max_f32_e32 v81, 0x1e3ce508, v81
	v_and_b32_e32 v85, 0xffff0000, v107
	v_pk_mul_f32 v[74:75], v[74:75], v[78:79]
	v_pk_mul_f32 v[78:79], v[70:71], v[80:81]
	v_max_f32_e32 v70, 0x1e3ce508, v84
	v_and_b32_e32 v95, 0xffff0000, v109
	v_max_f32_e32 v80, 0x1e3ce508, v94
	v_max_f32_e32 v71, 0x1e3ce508, v85
	v_max_f32_e32 v81, 0x1e3ce508, v95
	v_pk_mul_f32 v[76:77], v[76:77], v[70:71]
	v_pk_mul_f32 v[80:81], v[72:73], v[80:81]
	s_mov_b64 s[26:27], 0x90
	v_cvt_pk_bf16_f32 v70, v74, v75
	v_cvt_pk_bf16_f32 v71, v76, v77
	v_cvt_pk_bf16_f32 v72, v78, v79
	v_cvt_pk_bf16_f32 v73, v80, v81
	v_lshl_add_u64 v[80:81], v[184:185], 0, s[26:27]
	global_store_dwordx4 v[82:83], v[70:73], off offset:256
	s_waitcnt vmcnt(3)
	v_lshlrev_b32_e32 v3, 16, v86
	v_mad_u64_u32 v[70:71], s[26:27], v80, s83, v[146:147]
	v_mad_i32_i24 v71, v81, s83, v71
	v_lshl_add_u64 v[82:83], v[70:71], 0, v[4:5]
	v_add_co_u32_e32 v72, vcc, s71, v82
	v_lshl_add_u64 v[70:71], v[82:83], 0, s[28:29]
	s_nop 0
	v_addc_co_u32_e32 v73, vcc, 0, v83, vcc
	global_load_dwordx4 v[72:75], v[72:73], off
	s_nop 0
	global_load_dwordx4 v[76:79], v[70:71], off offset:256
	v_and_b32_e32 v85, 0xffff0000, v86
	v_lshlrev_b32_e32 v86, 16, v88
	v_max_f32_e32 v84, 0x1e3ce508, v3
	v_lshlrev_b32_e32 v94, 16, v87
	v_and_b32_e32 v95, 0xffff0000, v87
	v_and_b32_e32 v87, 0xffff0000, v88
	v_max_f32_e32 v86, 0x1e3ce508, v86
	v_max_f32_e32 v85, 0x1e3ce508, v85
	v_lshlrev_b32_e32 v88, 16, v89
	v_max_f32_e32 v87, 0x1e3ce508, v87
	v_pk_mul_f32 v[66:67], v[66:67], v[84:85]
	v_pk_mul_f32 v[84:85], v[62:63], v[86:87]
	v_max_f32_e32 v62, 0x1e3ce508, v94
	v_and_b32_e32 v89, 0xffff0000, v89
	v_max_f32_e32 v86, 0x1e3ce508, v88
	s_mov_b64 s[26:27], 0x80000
	v_max_f32_e32 v63, 0x1e3ce508, v95
	v_lshl_add_u64 v[70:71], v[148:149], 0, s[26:27]
	v_max_f32_e32 v87, 0x1e3ce508, v89
	v_pk_mul_f32 v[68:69], v[68:69], v[62:63]
	v_pk_mul_f32 v[86:87], v[64:65], v[86:87]
	v_cvt_pk_bf16_f32 v62, v66, v67
	v_lshl_add_u64 v[66:67], s[18:19], 0, v[70:71]
	v_cvt_pk_bf16_f32 v63, v68, v69
	v_cvt_pk_bf16_f32 v64, v84, v85
	v_cvt_pk_bf16_f32 v65, v86, v87
	v_lshl_add_u64 v[66:67], v[66:67], 0, v[4:5]
	s_waitcnt vmcnt(4)
; __device__ __forceinline__ unsigned cvt_pk_bf16(float lo, float hi) { const f2_t_ v = {lo, hi}; return __builtin_bit_cast(unsigned, __builtin_convertvector(v, bf2_t_)); }
;     static __device__ __forceinline__ void unpack(const u32x4 g4, f32x4& g0, f32x4& g1) { g0 = (f32x4){bflo(g4.x), bfhi(g4.x), bflo(g4.y), bfhi(g4.y)}; g1 = (f32x4){bflo(g4.z), bfhi(g4.z), bflo(g4.w), bfhi(g4.w)}; }
;     __device__ __forceinline__ void operator()(const f32x4 (&acc)[2][2][4][2], const Unit& u, int wr, int wc, int fr, int fq) const {
;     ...
;             if (gi < 7) { const size_t row2 = r0 + ((gi + 1) >> 2) * HALF + ((gi + 1) & 3) * 16;
; #pragma unroll
;                 for (int bj = 0; bj < 2; ++bj) gw[(gi + 1) & 1][bj] = *(const u32x4*)(GT + row2 * ldg + 4096 + col0 + bj * HALF); }
;             asm volatile("" ::: "memory");
; #pragma unroll
;             for (int bj = 0; bj < 2; ++bj) {
;                 f32x4 g0, g1; unpack(gw[gi & 1][bj], g0, g1);
;                 f32x4 v0, v1;
; #pragma unroll
;                 for (int j = 0; j < 4; ++j) { v0[j] = acc[ai][bj][m][0][j] * fmaxf(g0[j], 1e-20f); v1[j] = acc[ai][bj][m][1][j] * fmaxf(g1[j], 1e-20f); }
;                 u32x4 w; w.x = cvt_pk_bf16(v0[0], v0[1]); w.y = cvt_pk_bf16(v0[2], v0[3]); w.z = cvt_pk_bf16(v1[0], v1[1]); w.w = cvt_pk_bf16(v1[2], v1[3]);
;                 *(u32x4*)(O + row * 2048 + col0 + bj * HALF) = w;
;             }
	v_lshlrev_b32_e32 v3, 16, v90
	global_store_dwordx4 v[66:67], v[62:65], off
	v_max_f32_e32 v3, v3, v3
	v_lshlrev_b32_e32 v68, 16, v91
	v_lshlrev_b32_e32 v64, 16, v92
	v_and_b32_e32 v63, 0xffff0000, v90
	v_max_f32_e32 v62, 0x1e3ce508, v3
	v_and_b32_e32 v65, 0xffff0000, v92
	v_max_f32_e32 v64, 0x1e3ce508, v64
	v_max_f32_e32 v63, 0x1e3ce508, v63
	v_lshlrev_b32_e32 v84, 16, v93
	v_max_f32_e32 v65, 0x1e3ce508, v65
	v_and_b32_e32 v69, 0xffff0000, v91
	v_pk_mul_f32 v[58:59], v[58:59], v[62:63]
	v_pk_mul_f32 v[62:63], v[54:55], v[64:65]
	v_max_f32_e32 v54, 0x1e3ce508, v68
	v_and_b32_e32 v85, 0xffff0000, v93
	v_max_f32_e32 v64, 0x1e3ce508, v84
	v_max_f32_e32 v55, 0x1e3ce508, v69
	v_max_f32_e32 v65, 0x1e3ce508, v85
	v_pk_mul_f32 v[60:61], v[60:61], v[54:55]
	v_pk_mul_f32 v[64:65], v[56:57], v[64:65]
	v_cvt_pk_bf16_f32 v54, v58, v59
	v_cvt_pk_bf16_f32 v55, v60, v61
	v_cvt_pk_bf16_f32 v56, v62, v63
	v_cvt_pk_bf16_f32 v57, v64, v65
	s_mov_b32 s26, 0x32000
	global_store_dwordx4 v[66:67], v[54:57], off offset:256
	v_lshl_add_u64 v[58:59], v[82:83], 0, s[30:31]
	v_lshlrev_b64 v[62:63], 12, v[80:81]
	v_add_co_u32_e32 v54, vcc, s26, v82
	s_mov_b64 s[26:27], -1
	s_nop 0
	v_addc_co_u32_e32 v55, vcc, 0, v83, vcc
	s_waitcnt vmcnt(3)
	v_lshlrev_b32_e32 v3, 16, v72
	v_lshlrev_b32_e32 v66, 16, v74
	v_max_f32_e32 v3, v3, v3
	v_and_b32_e32 v65, 0xffff0000, v72
	v_max_f32_e32 v64, 0x1e3ce508, v3
	global_load_dwordx4 v[54:57], v[54:55], off
	s_nop 0
	global_load_dwordx4 v[58:61], v[58:59], off offset:256
	v_and_b32_e32 v67, 0xffff0000, v74
	v_max_f32_e32 v66, 0x1e3ce508, v66
	v_lshlrev_b32_e32 v68, 16, v73
	v_max_f32_e32 v65, 0x1e3ce508, v65
	v_lshlrev_b32_e32 v72, 16, v75
	v_max_f32_e32 v67, 0x1e3ce508, v67
	v_and_b32_e32 v69, 0xffff0000, v73
	v_pk_mul_f32 v[50:51], v[50:51], v[64:65]
	v_pk_mul_f32 v[64:65], v[46:47], v[66:67]
	v_max_f32_e32 v46, 0x1e3ce508, v68
	v_and_b32_e32 v73, 0xffff0000, v75
	v_max_f32_e32 v66, 0x1e3ce508, v72
	v_max_f32_e32 v47, 0x1e3ce508, v69
	v_max_f32_e32 v67, 0x1e3ce508, v73
	v_pk_mul_f32 v[52:53], v[52:53], v[46:47]
	v_pk_mul_f32 v[66:67], v[48:49], v[66:67]
	v_cvt_pk_bf16_f32 v46, v50, v51
	v_lshl_add_u64 v[50:51], s[18:19], 0, v[62:63]
	v_cvt_pk_bf16_f32 v47, v52, v53
	v_cvt_pk_bf16_f32 v48, v64, v65
	v_cvt_pk_bf16_f32 v49, v66, v67
	v_lshl_add_u64 v[50:51], v[50:51], 0, v[4:5]
	s_waitcnt vmcnt(4)
	v_lshlrev_b32_e32 v3, 16, v76
	global_store_dwordx4 v[50:51], v[46:49], off
	v_max_f32_e32 v3, v3, v3
	v_lshlrev_b32_e32 v52, 16, v77
	v_lshlrev_b32_e32 v48, 16, v78
	v_and_b32_e32 v47, 0xffff0000, v76
	v_max_f32_e32 v46, 0x1e3ce508, v3
	v_and_b32_e32 v49, 0xffff0000, v78
	v_max_f32_e32 v48, 0x1e3ce508, v48
	v_max_f32_e32 v47, 0x1e3ce508, v47
	v_lshlrev_b32_e32 v62, 16, v79
	v_max_f32_e32 v49, 0x1e3ce508, v49
	v_and_b32_e32 v53, 0xffff0000, v77
	v_pk_mul_f32 v[42:43], v[42:43], v[46:47]
	v_pk_mul_f32 v[46:47], v[38:39], v[48:49]
	v_max_f32_e32 v38, 0x1e3ce508, v52
	v_and_b32_e32 v63, 0xffff0000, v79
	v_max_f32_e32 v48, 0x1e3ce508, v62
	v_max_f32_e32 v39, 0x1e3ce508, v53
	v_max_f32_e32 v49, 0x1e3ce508, v63
	v_pk_mul_f32 v[44:45], v[44:45], v[38:39]
	v_pk_mul_f32 v[48:49], v[40:41], v[48:49]
	v_cvt_pk_bf16_f32 v38, v42, v43
	v_cvt_pk_bf16_f32 v39, v44, v45
	v_cvt_pk_bf16_f32 v40, v46, v47
	v_cvt_pk_bf16_f32 v41, v48, v49
	global_store_dwordx4 v[50:51], v[38:41], off offset:256
	v_lshl_add_u64 v[42:43], v[82:83], 0, s[60:61]
	v_or_b32_e32 v46, 0x20000, v70
	v_add_co_u32_e32 v38, vcc, s73, v82
	v_mov_b32_e32 v47, v71
	s_nop 0
	v_addc_co_u32_e32 v39, vcc, 0, v83, vcc
	global_load_dwordx4 v[38:41], v[38:39], off
	s_nop 0
	global_load_dwordx4 v[42:45], v[42:43], off offset:256
	v_or_b32_e32 v70, 0x30000, v70
	s_and_b64 vcc, exec, s[2:3]
	s_waitcnt vmcnt(5)
; __device__ __forceinline__ unsigned cvt_pk_bf16(float lo, float hi) { const f2_t_ v = {lo, hi}; return __builtin_bit_cast(unsigned, __builtin_convertvector(v, bf2_t_)); }
;     static __device__ __forceinline__ void unpack(const u32x4 g4, f32x4& g0, f32x4& g1) { g0 = (f32x4){bflo(g4.x), bfhi(g4.x), bflo(g4.y), bfhi(g4.y)}; g1 = (f32x4){bflo(g4.z), bfhi(g4.z), bflo(g4.w), bfhi(g4.w)}; }
;     __device__ __forceinline__ void operator()(const f32x4 (&acc)[2][2][4][2], const Unit& u, int wr, int wc, int fr, int fq) const {
;     ...
;         for (int gi = 0; gi < 8; ++gi) {
;             const int ai = gi >> 2, m = gi & 3; const size_t row = r0 + ai * HALF + m * 16;
;             if (gi < 7) { const size_t row2 = r0 + ((gi + 1) >> 2) * HALF + ((gi + 1) & 3) * 16;
; #pragma unroll
;                 for (int bj = 0; bj < 2; ++bj) gw[(gi + 1) & 1][bj] = *(const u32x4*)(GT + row2 * ldg + 4096 + col0 + bj * HALF); }
;             asm volatile("" ::: "memory");
; #pragma unroll
;             for (int bj = 0; bj < 2; ++bj) {
;                 f32x4 g0, g1; unpack(gw[gi & 1][bj], g0, g1);
;                 f32x4 v0, v1;
; #pragma unroll
;                 for (int j = 0; j < 4; ++j) { v0[j] = acc[ai][bj][m][0][j] * fmaxf(g0[j], 1e-20f); v1[j] = acc[ai][bj][m][1][j] * fmaxf(g1[j], 1e-20f); }
;                 u32x4 w; w.x = cvt_pk_bf16(v0[0], v0[1]); w.y = cvt_pk_bf16(v0[2], v0[3]); w.z = cvt_pk_bf16(v1[0], v1[1]); w.w = cvt_pk_bf16(v1[2], v1[3]);
;                 *(u32x4*)(O + row * 2048 + col0 + bj * HALF) = w;
;             }
	v_lshlrev_b32_e32 v3, 16, v54
	v_lshlrev_b32_e32 v50, 16, v56
	v_and_b32_e32 v49, 0xffff0000, v54
	v_max_f32_e32 v48, 0x1e3ce508, v3
	v_and_b32_e32 v51, 0xffff0000, v56
	v_max_f32_e32 v50, 0x1e3ce508, v50
	v_lshlrev_b32_e32 v52, 16, v55
	v_max_f32_e32 v49, 0x1e3ce508, v49
	v_lshlrev_b32_e32 v54, 16, v57
	v_max_f32_e32 v51, 0x1e3ce508, v51
	v_and_b32_e32 v53, 0xffff0000, v55
	v_pk_mul_f32 v[34:35], v[34:35], v[48:49]
	v_pk_mul_f32 v[48:49], v[30:31], v[50:51]
	v_max_f32_e32 v30, 0x1e3ce508, v52
	v_and_b32_e32 v55, 0xffff0000, v57
	v_max_f32_e32 v50, 0x1e3ce508, v54
	v_max_f32_e32 v31, 0x1e3ce508, v53
	v_max_f32_e32 v51, 0x1e3ce508, v55
	v_pk_mul_f32 v[36:37], v[36:37], v[30:31]
	v_pk_mul_f32 v[50:51], v[32:33], v[50:51]
	v_cvt_pk_bf16_f32 v30, v34, v35
	v_lshl_add_u64 v[34:35], s[18:19], 0, v[46:47]
	v_cvt_pk_bf16_f32 v31, v36, v37
	v_cvt_pk_bf16_f32 v32, v48, v49
	v_cvt_pk_bf16_f32 v33, v50, v51
	v_lshl_add_u64 v[34:35], v[34:35], 0, v[4:5]
	s_waitcnt vmcnt(4)
	v_lshlrev_b32_e32 v3, 16, v58
	global_store_dwordx4 v[34:35], v[30:33], off
	v_max_f32_e32 v3, v3, v3
	v_lshlrev_b32_e32 v36, 16, v59
	v_lshlrev_b32_e32 v32, 16, v60
	v_and_b32_e32 v31, 0xffff0000, v58
	v_max_f32_e32 v30, 0x1e3ce508, v3
	v_and_b32_e32 v33, 0xffff0000, v60
	v_max_f32_e32 v32, 0x1e3ce508, v32
	v_max_f32_e32 v31, 0x1e3ce508, v31
	v_lshlrev_b32_e32 v46, 16, v61
	v_max_f32_e32 v33, 0x1e3ce508, v33
	v_and_b32_e32 v37, 0xffff0000, v59
	v_pk_mul_f32 v[26:27], v[26:27], v[30:31]
	v_pk_mul_f32 v[30:31], v[22:23], v[32:33]
	v_max_f32_e32 v22, 0x1e3ce508, v36
	v_and_b32_e32 v47, 0xffff0000, v61
	v_max_f32_e32 v32, 0x1e3ce508, v46
	v_max_f32_e32 v23, 0x1e3ce508, v37
	v_max_f32_e32 v33, 0x1e3ce508, v47
	v_pk_mul_f32 v[28:29], v[28:29], v[22:23]
	v_pk_mul_f32 v[32:33], v[24:25], v[32:33]
	v_cvt_pk_bf16_f32 v22, v26, v27
	v_cvt_pk_bf16_f32 v23, v28, v29
	v_cvt_pk_bf16_f32 v24, v30, v31
	v_cvt_pk_bf16_f32 v25, v32, v33
	global_store_dwordx4 v[34:35], v[22:25], off offset:256
	s_waitcnt vmcnt(3)
	v_lshlrev_b32_e32 v3, 16, v38
	s_nop 0
	v_lshlrev_b32_e32 v24, 16, v40
	v_max_f32_e32 v3, v3, v3
	v_and_b32_e32 v23, 0xffff0000, v38
	v_max_f32_e32 v22, 0x1e3ce508, v3
	v_and_b32_e32 v25, 0xffff0000, v40
	v_max_f32_e32 v24, 0x1e3ce508, v24
	v_lshlrev_b32_e32 v26, 16, v39
	v_max_f32_e32 v23, 0x1e3ce508, v23
	v_lshlrev_b32_e32 v28, 16, v41
	v_max_f32_e32 v25, 0x1e3ce508, v25
	v_and_b32_e32 v27, 0xffff0000, v39
	v_pk_mul_f32 v[18:19], v[18:19], v[22:23]
	v_pk_mul_f32 v[22:23], v[14:15], v[24:25]
	v_max_f32_e32 v14, 0x1e3ce508, v26
	v_and_b32_e32 v29, 0xffff0000, v41
	v_max_f32_e32 v24, 0x1e3ce508, v28
	v_max_f32_e32 v15, 0x1e3ce508, v27
	v_max_f32_e32 v25, 0x1e3ce508, v29
	v_pk_mul_f32 v[20:21], v[20:21], v[14:15]
	v_pk_mul_f32 v[24:25], v[16:17], v[24:25]
	v_cvt_pk_bf16_f32 v14, v18, v19
	v_lshl_add_u64 v[18:19], s[18:19], 0, v[70:71]
	v_cvt_pk_bf16_f32 v15, v20, v21
	v_cvt_pk_bf16_f32 v16, v22, v23
	v_cvt_pk_bf16_f32 v17, v24, v25
	v_lshl_add_u64 v[18:19], v[18:19], 0, v[4:5]
	s_waitcnt vmcnt(2)
	v_lshlrev_b32_e32 v3, 16, v42
	global_store_dwordx4 v[18:19], v[14:17], off
	v_max_f32_e32 v3, v3, v3
	v_and_b32_e32 v5, 0xffff0000, v42
	v_lshlrev_b32_e32 v14, 16, v44
	v_max_f32_e32 v4, 0x1e3ce508, v3
	v_max_f32_e32 v3, v14, v14
	v_and_b32_e32 v15, 0xffff0000, v44
	v_max_f32_e32 v14, 0x1e3ce508, v3
	v_lshlrev_b32_e32 v16, 16, v43
	v_max_f32_e32 v5, 0x1e3ce508, v5
	v_lshlrev_b32_e32 v20, 16, v45
	v_max_f32_e32 v15, 0x1e3ce508, v15
	v_and_b32_e32 v17, 0xffff0000, v43
	v_pk_mul_f32 v[4:5], v[10:11], v[4:5]
	v_max_f32_e32 v10, 0x1e3ce508, v16
	v_and_b32_e32 v21, 0xffff0000, v45
	v_pk_mul_f32 v[6:7], v[6:7], v[14:15]
	v_max_f32_e32 v14, 0x1e3ce508, v20
	v_max_f32_e32 v11, 0x1e3ce508, v17
	v_max_f32_e32 v3, v21, v21
	v_max_f32_e32 v15, 0x1e3ce508, v3
	v_pk_mul_f32 v[10:11], v[12:13], v[10:11]
	v_pk_mul_f32 v[8:9], v[8:9], v[14:15]
	v_cvt_pk_bf16_f32 v4, v4, v5
	v_cvt_pk_bf16_f32 v5, v10, v11
	v_cvt_pk_bf16_f32 v6, v6, v7
	v_cvt_pk_bf16_f32 v7, v8, v9
	global_store_dwordx4 v[18:19], v[4:7], off offset:256
	s_cbranch_vccnz .LBB0_980
	s_andn2_b64 vcc, exec, s[14:15]
	s_cbranch_vccnz .LBB0_979
	s_barrier
	s_branch .LBB0_979
